# GEMM K-loops: removed the compiler-duplicated lgkmcnt(0) after each pre-MFMA barrier (the inline-asm wait before the barrier already drained LDS) in all six SP2 mainloops
# speedup vs baseline: 1.0186x; 1.0064x over previous
; #define PG8_STAGE(bufoff, gbase, voff) do { _Pragma("unroll") for (int _i = 0; _i < 2; ++_i) \
;         __builtin_amdgcn_global_load_lds((const unsigned*)((const char*)(gbase) + (voff)[_i]), (LAS unsigned*)(lds + (bufoff) + ldsw + _i * 8192), 16, 0, 0); } while (0)
; #define PG8_LDA(dst, b, h) do { _Pragma("unroll") for (int m = 0; m < 4; ++m) _Pragma("unroll") for (int k = 0; k < 2; ++k) dst[m][k] = *(const LAS bf16x8*)(lds + PG8_SA(b, h) + aoff + m * 2048 + k * 1024); } while (0)
; #define PG8_LDB(dst, b, h) do { _Pragma("unroll") for (int n = 0; n < 2; ++n) _Pragma("unroll") for (int k = 0; k < 2; ++k) dst[n][k] = *(const LAS bf16x8*)(lds + PG8_SB(b, h) + boff + n * 2048 + k * 1024); } while (0)
; #define PG8_MMA(ai, bj, At, Bt) do { __builtin_amdgcn_s_setprio(1); _Pragma("unroll") for (int m = 0; m < 4; ++m) _Pragma("unroll") for (int n = 0; n < 2; ++n) _Pragma("unroll") for (int k = 0; k < 2; ++k) \
;         acc[ai][bj][m][n] = __builtin_amdgcn_mfma_f32_16x16x32_bf16(Bt[n][k], At[m][k], acc[ai][bj][m][n], 0, 0, 0); __builtin_amdgcn_s_setprio(0); } while (0)
; #define PG8_WAIT_V(n) asm volatile("s_waitcnt vmcnt(" #n ")" ::: "memory")
; #define PG8_WAIT_L(n) asm volatile("s_waitcnt lgkmcnt(" #n ")" ::: "memory")
; #define PG8_BAR __builtin_amdgcn_s_barrier()
; #define PG8_SCHED __builtin_amdgcn_sched_barrier(0)
; template <class Epi, class Sched = StaticOrder, class EpiSub = NoSub, bool FAST = false>
; __device__ __forceinline__ void gemm_phase(LAS unsigned char* lds, const Gemm g, const Sched& S, const Epi& E, const EpiSub& ES = EpiSub()) {
;     ...
;             PG8_LDB(B0, 0, 0); PG8_LDB(B1, 0, 1); PG8_SCHED; PG8_LDA(At, 0, 0); PG8_STAGE(PG8_SA(1, 1), a1 + hstepA, voffA);
;             PG8_WAIT_V(8); PG8_WAIT_L(0); PG8_BAR; PG8_MMA(0, 0, At, B0); PG8_MMA(0, 1, At, B1); PG8_BAR; PG8_SCHED;
;             PG8_LDA(At, 0, 1); PG8_STAGE(PG8_SB(0, 0), b2, voffB); PG8_STAGE(PG8_SB(0, 1), b2 + hstepB, voffB); PG8_STAGE(PG8_SA(0, 0), a2, voffA);
;             PG8_WAIT_V(8); PG8_WAIT_L(0); PG8_BAR; PG8_MMA(1, 0, At, B0); PG8_MMA(1, 1, At, B1); PG8_BAR; PG8_SCHED;
.LBB0_216:
	ds_read_b128 v[154:157], v150
	ds_read_b128 v[158:161], v150 offset:1024
	ds_read_b128 v[162:165], v150 offset:2048
	ds_read_b128 v[166:169], v150 offset:3072
	ds_read_b128 v[170:173], v151
	ds_read_b128 v[174:177], v151 offset:1024
	ds_read_b128 v[178:181], v151 offset:2048
	ds_read_b128 v[182:185], v151 offset:3072
	s_add_u32 s24, s22, 0xfff80080
	s_addc_u32 s25, s23, -1
	s_cmp_eq_u32 s50, 28
	s_cselect_b32 s27, s2, s25
	s_cselect_b32 s26, s3, s24
	s_cselect_b32 s25, s13, s49
	s_cselect_b32 s24, s15, s48
	v_lshl_add_u64 v[144:145], s[22:23], 0, v[136:137]
	s_add_i32 m0, s21, 0xc000
	ds_read_b128 v[186:189], v152
	ds_read_b128 v[194:197], v152 offset:1024
	ds_read_b128 v[198:201], v152 offset:2048
	ds_read_b128 v[202:205], v152 offset:3072
	ds_read_b128 v[206:209], v152 offset:4096
	ds_read_b128 v[210:213], v152 offset:5120
	ds_read_b128 v[214:217], v152 offset:6144
	ds_read_b128 v[218:221], v152 offset:7168
	global_load_lds_dwordx4 v[144:145], off
	v_lshl_add_u64 v[144:145], s[22:23], 0, v[138:139]
	s_add_i32 m0, s21, 0xe000
	s_nop 0
	global_load_lds_dwordx4 v[144:145], off
	s_waitcnt vmcnt(8)
	s_waitcnt lgkmcnt(0)
	s_barrier
	s_setprio 1
	v_mfma_f32_16x16x32_bf16 v[124:127], v[154:157], v[186:189], v[124:127]
	v_mfma_f32_16x16x32_bf16 v[120:123], v[162:165], v[186:189], v[120:123]
	v_mfma_f32_16x16x32_bf16 v[116:119], v[154:157], v[198:201], v[116:119]
	v_mfma_f32_16x16x32_bf16 v[108:111], v[162:165], v[198:201], v[108:111]
	v_mfma_f32_16x16x32_bf16 v[100:103], v[154:157], v[206:209], v[100:103]
	v_mfma_f32_16x16x32_bf16 v[92:95], v[162:165], v[206:209], v[92:95]
	v_mfma_f32_16x16x32_bf16 v[84:87], v[154:157], v[214:217], v[84:87]
	v_mfma_f32_16x16x32_bf16 v[76:79], v[162:165], v[214:217], v[76:79]
	v_mfma_f32_16x16x32_bf16 v[124:127], v[158:161], v[194:197], v[124:127]
	v_mfma_f32_16x16x32_bf16 v[120:123], v[166:169], v[194:197], v[120:123]
	v_mfma_f32_16x16x32_bf16 v[116:119], v[158:161], v[202:205], v[116:119]
	v_mfma_f32_16x16x32_bf16 v[108:111], v[166:169], v[202:205], v[108:111]
	v_mfma_f32_16x16x32_bf16 v[100:103], v[158:161], v[210:213], v[100:103]
	v_mfma_f32_16x16x32_bf16 v[92:95], v[166:169], v[210:213], v[92:95]
	v_mfma_f32_16x16x32_bf16 v[84:87], v[158:161], v[218:221], v[84:87]
	v_mfma_f32_16x16x32_bf16 v[76:79], v[166:169], v[218:221], v[76:79]
	s_setprio 0
	s_setprio 1
	v_mfma_f32_16x16x32_bf16 v[112:115], v[170:173], v[186:189], v[112:115]
	v_mfma_f32_16x16x32_bf16 v[104:107], v[178:181], v[186:189], v[104:107]
	v_mfma_f32_16x16x32_bf16 v[96:99], v[170:173], v[198:201], v[96:99]
	v_mfma_f32_16x16x32_bf16 v[88:91], v[178:181], v[198:201], v[88:91]
	v_mfma_f32_16x16x32_bf16 v[80:83], v[170:173], v[206:209], v[80:83]
	v_mfma_f32_16x16x32_bf16 v[72:75], v[178:181], v[206:209], v[72:75]
	v_mfma_f32_16x16x32_bf16 v[68:71], v[170:173], v[214:217], v[68:71]
	v_mfma_f32_16x16x32_bf16 v[64:67], v[178:181], v[214:217], v[64:67]
	v_mfma_f32_16x16x32_bf16 v[112:115], v[174:177], v[194:197], v[112:115]
	v_mfma_f32_16x16x32_bf16 v[104:107], v[182:185], v[194:197], v[104:107]
	v_mfma_f32_16x16x32_bf16 v[96:99], v[174:177], v[202:205], v[96:99]
	v_mfma_f32_16x16x32_bf16 v[88:91], v[182:185], v[202:205], v[88:91]
	v_mfma_f32_16x16x32_bf16 v[80:83], v[174:177], v[210:213], v[80:83]
	v_mfma_f32_16x16x32_bf16 v[72:75], v[182:185], v[210:213], v[72:75]
	v_mfma_f32_16x16x32_bf16 v[68:71], v[174:177], v[218:221], v[68:71]
	v_mfma_f32_16x16x32_bf16 v[64:67], v[182:185], v[218:221], v[64:67]
	s_setprio 0
	s_barrier
	s_add_i32 s51, s41, s30
	v_lshl_add_u64 v[144:145], s[24:25], 0, v[130:131]
	s_mov_b32 m0, s51
	ds_read_b128 v[186:189], v152 offset:16384
	ds_read_b128 v[194:197], v152 offset:17408
	ds_read_b128 v[198:201], v152 offset:18432
	ds_read_b128 v[202:205], v152 offset:19456
	ds_read_b128 v[206:209], v152 offset:20480
	ds_read_b128 v[210:213], v152 offset:21504
	ds_read_b128 v[214:217], v152 offset:22528
	ds_read_b128 v[218:221], v152 offset:23552
	global_load_lds_dwordx4 v[144:145], off
	s_add_i32 m0, s51, 0x2000
	s_add_u32 s68, s24, 0x80000
	v_lshl_add_u64 v[190:191], s[24:25], 0, v[134:135]
	s_addc_u32 s69, s25, 0
	s_add_i32 s51, s42, s30
	global_load_lds_dwordx4 v[190:191], off
	v_lshl_add_u64 v[222:223], s[68:69], 0, v[130:131]
	s_mov_b32 m0, s51
	v_lshl_add_u64 v[224:225], s[26:27], 0, v[132:133]
	global_load_lds_dwordx4 v[222:223], off
	v_lshl_add_u64 v[222:223], s[68:69], 0, v[134:135]
	s_add_i32 m0, s51, 0x2000
	s_nop 0
	global_load_lds_dwordx4 v[222:223], off
	v_lshl_add_u64 v[222:223], s[26:27], 0, v[128:129]
	s_mov_b32 m0, s21
	s_nop 0
	global_load_lds_dwordx4 v[222:223], off
	s_mov_b32 m0, s34
	s_nop 0
	global_load_lds_dwordx4 v[224:225], off
	s_waitcnt vmcnt(8)
	s_waitcnt lgkmcnt(0)
	s_barrier
; #define PG8_STAGE(bufoff, gbase, voff) do { _Pragma("unroll") for (int _i = 0; _i < 2; ++_i) \
;         __builtin_amdgcn_global_load_lds((const unsigned*)((const char*)(gbase) + (voff)[_i]), (LAS unsigned*)(lds + (bufoff) + ldsw + _i * 8192), 16, 0, 0); } while (0)
; #define PG8_LDA(dst, b, h) do { _Pragma("unroll") for (int m = 0; m < 4; ++m) _Pragma("unroll") for (int k = 0; k < 2; ++k) dst[m][k] = *(const LAS bf16x8*)(lds + PG8_SA(b, h) + aoff + m * 2048 + k * 1024); } while (0)
; #define PG8_LDB(dst, b, h) do { _Pragma("unroll") for (int n = 0; n < 2; ++n) _Pragma("unroll") for (int k = 0; k < 2; ++k) dst[n][k] = *(const LAS bf16x8*)(lds + PG8_SB(b, h) + boff + n * 2048 + k * 1024); } while (0)
; #define PG8_MMA(ai, bj, At, Bt) do { __builtin_amdgcn_s_setprio(1); _Pragma("unroll") for (int m = 0; m < 4; ++m) _Pragma("unroll") for (int n = 0; n < 2; ++n) _Pragma("unroll") for (int k = 0; k < 2; ++k) \
;         acc[ai][bj][m][n] = __builtin_amdgcn_mfma_f32_16x16x32_bf16(Bt[n][k], At[m][k], acc[ai][bj][m][n], 0, 0, 0); __builtin_amdgcn_s_setprio(0); } while (0)
; #define PG8_WAIT_V(n) asm volatile("s_waitcnt vmcnt(" #n ")" ::: "memory")
; #define PG8_WAIT_L(n) asm volatile("s_waitcnt lgkmcnt(" #n ")" ::: "memory")
; #define PG8_BAR __builtin_amdgcn_s_barrier()
; #define PG8_SCHED __builtin_amdgcn_sched_barrier(0)
; template <class Epi, class Sched = StaticOrder, class EpiSub = NoSub, bool FAST = false>
; __device__ __forceinline__ void gemm_phase(LAS unsigned char* lds, const Gemm g, const Sched& S, const Epi& E, const EpiSub& ES = EpiSub()) {
;     ...
;             PG8_WAIT_V(8); PG8_WAIT_L(0); PG8_BAR; PG8_MMA(1, 0, At, B0); PG8_MMA(1, 1, At, B1); PG8_BAR; PG8_SCHED;
;             PG8_LDB(B0, 1, 0); PG8_LDB(B1, 1, 1); PG8_SCHED; PG8_LDA(At, 1, 0); PG8_STAGE(PG8_SA(0, 1), a2 + hstepA, voffA);
;             PG8_WAIT_V(8); PG8_WAIT_L(0); PG8_BAR; PG8_MMA(0, 0, At, B0); PG8_MMA(0, 1, At, B1); PG8_BAR; PG8_SCHED;
	s_setprio 1
	v_mfma_f32_16x16x32_bf16 v[60:63], v[154:157], v[186:189], v[60:63]
	v_mfma_f32_16x16x32_bf16 v[56:59], v[162:165], v[186:189], v[56:59]
	v_mfma_f32_16x16x32_bf16 v[52:55], v[154:157], v[198:201], v[52:55]
	v_mfma_f32_16x16x32_bf16 v[44:47], v[162:165], v[198:201], v[44:47]
	v_mfma_f32_16x16x32_bf16 v[36:39], v[154:157], v[206:209], v[36:39]
	v_mfma_f32_16x16x32_bf16 v[28:31], v[162:165], v[206:209], v[28:31]
	v_mfma_f32_16x16x32_bf16 v[20:23], v[154:157], v[214:217], v[20:23]
	v_mfma_f32_16x16x32_bf16 v[12:15], v[162:165], v[214:217], v[12:15]
	v_mfma_f32_16x16x32_bf16 v[60:63], v[158:161], v[194:197], v[60:63]
	v_mfma_f32_16x16x32_bf16 v[56:59], v[166:169], v[194:197], v[56:59]
	v_mfma_f32_16x16x32_bf16 v[52:55], v[158:161], v[202:205], v[52:55]
	v_mfma_f32_16x16x32_bf16 v[44:47], v[166:169], v[202:205], v[44:47]
	v_mfma_f32_16x16x32_bf16 v[36:39], v[158:161], v[210:213], v[36:39]
	v_mfma_f32_16x16x32_bf16 v[28:31], v[166:169], v[210:213], v[28:31]
	v_mfma_f32_16x16x32_bf16 v[20:23], v[158:161], v[218:221], v[20:23]
	v_mfma_f32_16x16x32_bf16 v[12:15], v[166:169], v[218:221], v[12:15]
	s_setprio 0
	s_setprio 1
	v_mfma_f32_16x16x32_bf16 v[48:51], v[170:173], v[186:189], v[48:51]
	v_mfma_f32_16x16x32_bf16 v[40:43], v[178:181], v[186:189], v[40:43]
	v_mfma_f32_16x16x32_bf16 v[32:35], v[170:173], v[198:201], v[32:35]
	v_mfma_f32_16x16x32_bf16 v[24:27], v[178:181], v[198:201], v[24:27]
	v_mfma_f32_16x16x32_bf16 v[16:19], v[170:173], v[206:209], v[16:19]
	v_mfma_f32_16x16x32_bf16 v[8:11], v[178:181], v[206:209], v[8:11]
	v_mfma_f32_16x16x32_bf16 v[4:7], v[170:173], v[214:217], v[4:7]
	v_mfma_f32_16x16x32_bf16 v[0:3], v[178:181], v[214:217], v[0:3]
	v_mfma_f32_16x16x32_bf16 v[48:51], v[174:177], v[194:197], v[48:51]
	v_mfma_f32_16x16x32_bf16 v[40:43], v[182:185], v[194:197], v[40:43]
	v_mfma_f32_16x16x32_bf16 v[32:35], v[174:177], v[202:205], v[32:35]
	v_mfma_f32_16x16x32_bf16 v[24:27], v[182:185], v[202:205], v[24:27]
	v_mfma_f32_16x16x32_bf16 v[16:19], v[174:177], v[210:213], v[16:19]
	v_mfma_f32_16x16x32_bf16 v[8:11], v[182:185], v[210:213], v[8:11]
	v_mfma_f32_16x16x32_bf16 v[4:7], v[174:177], v[218:221], v[4:7]
	v_mfma_f32_16x16x32_bf16 v[0:3], v[182:185], v[218:221], v[0:3]
	s_setprio 0
	s_barrier
	s_add_i32 s51, 0, 0x18000
	v_add_u32_e32 v153, s51, v148
	s_add_i32 s68, 0, 0x1c000
	ds_read_b128 v[154:157], v153
	ds_read_b128 v[158:161], v153 offset:1024
	ds_read_b128 v[162:165], v153 offset:2048
	ds_read_b128 v[166:169], v153 offset:3072
	v_add_u32_e32 v153, s68, v148
	ds_read_b128 v[170:173], v153
	ds_read_b128 v[174:177], v153 offset:1024
	ds_read_b128 v[178:181], v153 offset:2048
	ds_read_b128 v[182:185], v153 offset:3072
	s_add_u32 s26, s26, 0x80000
	s_addc_u32 s27, s27, 0
	s_mov_b32 m0, s35
	v_lshl_add_u64 v[226:227], s[26:27], 0, v[128:129]
	ds_read_b128 v[186:189], v152 offset:32768
	ds_read_b128 v[194:197], v152 offset:33792
	ds_read_b128 v[198:201], v152 offset:34816
	ds_read_b128 v[202:205], v152 offset:35840
	ds_read_b128 v[206:209], v152 offset:36864
	ds_read_b128 v[210:213], v152 offset:37888
	ds_read_b128 v[214:217], v152 offset:38912
	ds_read_b128 v[218:221], v152 offset:39936
	global_load_lds_dwordx4 v[226:227], off
	v_lshl_add_u64 v[226:227], s[26:27], 0, v[132:133]
	s_mov_b32 m0, s36
	s_nop 0
	global_load_lds_dwordx4 v[226:227], off
	s_waitcnt vmcnt(8)
	s_waitcnt lgkmcnt(0)
	s_barrier
	s_setprio 1
	v_mfma_f32_16x16x32_bf16 v[124:127], v[154:157], v[186:189], v[124:127]
	v_mfma_f32_16x16x32_bf16 v[120:123], v[162:165], v[186:189], v[120:123]
	v_mfma_f32_16x16x32_bf16 v[116:119], v[154:157], v[198:201], v[116:119]
	v_mfma_f32_16x16x32_bf16 v[108:111], v[162:165], v[198:201], v[108:111]
	v_mfma_f32_16x16x32_bf16 v[100:103], v[154:157], v[206:209], v[100:103]
	v_mfma_f32_16x16x32_bf16 v[92:95], v[162:165], v[206:209], v[92:95]
	v_mfma_f32_16x16x32_bf16 v[84:87], v[154:157], v[214:217], v[84:87]
	v_mfma_f32_16x16x32_bf16 v[76:79], v[162:165], v[214:217], v[76:79]
	v_mfma_f32_16x16x32_bf16 v[124:127], v[158:161], v[194:197], v[124:127]
	v_mfma_f32_16x16x32_bf16 v[120:123], v[166:169], v[194:197], v[120:123]
	v_mfma_f32_16x16x32_bf16 v[116:119], v[158:161], v[202:205], v[116:119]
	v_mfma_f32_16x16x32_bf16 v[108:111], v[166:169], v[202:205], v[108:111]
	v_mfma_f32_16x16x32_bf16 v[100:103], v[158:161], v[210:213], v[100:103]
	v_mfma_f32_16x16x32_bf16 v[92:95], v[166:169], v[210:213], v[92:95]
	v_mfma_f32_16x16x32_bf16 v[84:87], v[158:161], v[218:221], v[84:87]
	v_mfma_f32_16x16x32_bf16 v[76:79], v[166:169], v[218:221], v[76:79]
	s_setprio 0
	s_setprio 1
	v_mfma_f32_16x16x32_bf16 v[112:115], v[170:173], v[186:189], v[112:115]
	v_mfma_f32_16x16x32_bf16 v[104:107], v[178:181], v[186:189], v[104:107]
	v_mfma_f32_16x16x32_bf16 v[96:99], v[170:173], v[198:201], v[96:99]
	v_mfma_f32_16x16x32_bf16 v[88:91], v[178:181], v[198:201], v[88:91]
	v_mfma_f32_16x16x32_bf16 v[80:83], v[170:173], v[206:209], v[80:83]
	v_mfma_f32_16x16x32_bf16 v[72:75], v[178:181], v[206:209], v[72:75]
	v_mfma_f32_16x16x32_bf16 v[68:71], v[170:173], v[214:217], v[68:71]
	v_mfma_f32_16x16x32_bf16 v[64:67], v[178:181], v[214:217], v[64:67]
	v_mfma_f32_16x16x32_bf16 v[112:115], v[174:177], v[194:197], v[112:115]
	v_mfma_f32_16x16x32_bf16 v[104:107], v[182:185], v[194:197], v[104:107]
	v_mfma_f32_16x16x32_bf16 v[96:99], v[174:177], v[202:205], v[96:99]
	v_mfma_f32_16x16x32_bf16 v[88:91], v[182:185], v[202:205], v[88:91]
	v_mfma_f32_16x16x32_bf16 v[80:83], v[174:177], v[210:213], v[80:83]
	v_mfma_f32_16x16x32_bf16 v[72:75], v[182:185], v[210:213], v[72:75]
	v_mfma_f32_16x16x32_bf16 v[68:71], v[174:177], v[218:221], v[68:71]
	v_mfma_f32_16x16x32_bf16 v[64:67], v[182:185], v[218:221], v[64:67]
	s_setprio 0
	s_barrier
; #define PG8_STAGE(bufoff, gbase, voff) do { _Pragma("unroll") for (int _i = 0; _i < 2; ++_i) \
;         __builtin_amdgcn_global_load_lds((const unsigned*)((const char*)(gbase) + (voff)[_i]), (LAS unsigned*)(lds + (bufoff) + ldsw + _i * 8192), 16, 0, 0); } while (0)
; #define PG8_LDA(dst, b, h) do { _Pragma("unroll") for (int m = 0; m < 4; ++m) _Pragma("unroll") for (int k = 0; k < 2; ++k) dst[m][k] = *(const LAS bf16x8*)(lds + PG8_SA(b, h) + aoff + m * 2048 + k * 1024); } while (0)
; #define PG8_MMA(ai, bj, At, Bt) do { __builtin_amdgcn_s_setprio(1); _Pragma("unroll") for (int m = 0; m < 4; ++m) _Pragma("unroll") for (int n = 0; n < 2; ++n) _Pragma("unroll") for (int k = 0; k < 2; ++k) \
;         acc[ai][bj][m][n] = __builtin_amdgcn_mfma_f32_16x16x32_bf16(Bt[n][k], At[m][k], acc[ai][bj][m][n], 0, 0, 0); __builtin_amdgcn_s_setprio(0); } while (0)
; #define PG8_WAIT_V(n) asm volatile("s_waitcnt vmcnt(" #n ")" ::: "memory")
; #define PG8_WAIT_L(n) asm volatile("s_waitcnt lgkmcnt(" #n ")" ::: "memory")
; #define PG8_BAR __builtin_amdgcn_s_barrier()
; #define PG8_SCHED __builtin_amdgcn_sched_barrier(0)
; template <class Epi, class Sched = StaticOrder, class EpiSub = NoSub, bool FAST = false>
; __device__ __forceinline__ void gemm_phase(LAS unsigned char* lds, const Gemm g, const Sched& S, const Epi& E, const EpiSub& ES = EpiSub()) {
;     ...
;             PG8_LDA(At, 1, 1); PG8_STAGE(PG8_SB(1, 0), b3, voffB); PG8_STAGE(PG8_SB(1, 1), b3 + hstepB, voffB); PG8_STAGE(PG8_SA(1, 0), a3, voffA);
;             PG8_WAIT_V(8); PG8_WAIT_L(0); PG8_BAR; PG8_MMA(1, 0, At, B0); PG8_MMA(1, 1, At, B1); PG8_BAR; PG8_SCHED;
	s_add_i32 s26, s51, s30
	v_lshl_add_u64 v[144:145], v[144:145], 0, s[8:9]
	s_mov_b32 m0, s26
	ds_read_b128 v[186:189], v152 offset:49152
	ds_read_b128 v[194:197], v152 offset:50176
	ds_read_b128 v[198:201], v152 offset:51200
	ds_read_b128 v[202:205], v152 offset:52224
	ds_read_b128 v[206:209], v152 offset:53248
	ds_read_b128 v[210:213], v152 offset:54272
	ds_read_b128 v[214:217], v152 offset:55296
	ds_read_b128 v[218:221], v152 offset:56320
	global_load_lds_dwordx4 v[144:145], off
	s_add_i32 m0, s26, 0x2000
	s_add_u32 s24, s24, 0x80080
	v_lshl_add_u64 v[144:145], v[190:191], 0, s[8:9]
	s_addc_u32 s25, s25, 0
	s_add_i32 s26, s68, s30
	global_load_lds_dwordx4 v[144:145], off
	v_lshl_add_u64 v[144:145], s[24:25], 0, v[130:131]
	s_mov_b32 m0, s26
	s_nop 0
	global_load_lds_dwordx4 v[144:145], off
	v_lshl_add_u64 v[144:145], s[24:25], 0, v[134:135]
	s_add_i32 m0, s26, 0x2000
	s_nop 0
	global_load_lds_dwordx4 v[144:145], off
	v_lshl_add_u64 v[144:145], v[222:223], 0, s[8:9]
	s_mov_b32 m0, s39
	s_nop 0
	global_load_lds_dwordx4 v[144:145], off
	v_lshl_add_u64 v[144:145], v[224:225], 0, s[8:9]
	s_mov_b32 m0, s40
	s_nop 0
	global_load_lds_dwordx4 v[144:145], off
	s_waitcnt vmcnt(8)
	s_waitcnt lgkmcnt(0)
	s_barrier
	s_setprio 1
	v_mfma_f32_16x16x32_bf16 v[60:63], v[154:157], v[186:189], v[60:63]
	v_mfma_f32_16x16x32_bf16 v[56:59], v[162:165], v[186:189], v[56:59]
	v_mfma_f32_16x16x32_bf16 v[52:55], v[154:157], v[198:201], v[52:55]
	v_mfma_f32_16x16x32_bf16 v[44:47], v[162:165], v[198:201], v[44:47]
	v_mfma_f32_16x16x32_bf16 v[36:39], v[154:157], v[206:209], v[36:39]
	v_mfma_f32_16x16x32_bf16 v[28:31], v[162:165], v[206:209], v[28:31]
	v_mfma_f32_16x16x32_bf16 v[20:23], v[154:157], v[214:217], v[20:23]
	v_mfma_f32_16x16x32_bf16 v[12:15], v[162:165], v[214:217], v[12:15]
	v_mfma_f32_16x16x32_bf16 v[60:63], v[158:161], v[194:197], v[60:63]
	v_mfma_f32_16x16x32_bf16 v[56:59], v[166:169], v[194:197], v[56:59]
	v_mfma_f32_16x16x32_bf16 v[52:55], v[158:161], v[202:205], v[52:55]
	v_mfma_f32_16x16x32_bf16 v[44:47], v[166:169], v[202:205], v[44:47]
	v_mfma_f32_16x16x32_bf16 v[36:39], v[158:161], v[210:213], v[36:39]
	v_mfma_f32_16x16x32_bf16 v[28:31], v[166:169], v[210:213], v[28:31]
	v_mfma_f32_16x16x32_bf16 v[20:23], v[158:161], v[218:221], v[20:23]
	v_mfma_f32_16x16x32_bf16 v[12:15], v[166:169], v[218:221], v[12:15]
	s_setprio 0
	s_setprio 1
	v_mfma_f32_16x16x32_bf16 v[48:51], v[170:173], v[186:189], v[48:51]
	v_mfma_f32_16x16x32_bf16 v[40:43], v[178:181], v[186:189], v[40:43]
	v_mfma_f32_16x16x32_bf16 v[32:35], v[170:173], v[198:201], v[32:35]
	v_mfma_f32_16x16x32_bf16 v[24:27], v[178:181], v[198:201], v[24:27]
	v_mfma_f32_16x16x32_bf16 v[16:19], v[170:173], v[206:209], v[16:19]
	v_mfma_f32_16x16x32_bf16 v[8:11], v[178:181], v[206:209], v[8:11]
	v_mfma_f32_16x16x32_bf16 v[4:7], v[170:173], v[214:217], v[4:7]
	v_mfma_f32_16x16x32_bf16 v[0:3], v[178:181], v[214:217], v[0:3]
	v_mfma_f32_16x16x32_bf16 v[48:51], v[174:177], v[194:197], v[48:51]
	v_mfma_f32_16x16x32_bf16 v[40:43], v[182:185], v[194:197], v[40:43]
	v_mfma_f32_16x16x32_bf16 v[32:35], v[174:177], v[202:205], v[32:35]
	v_mfma_f32_16x16x32_bf16 v[24:27], v[182:185], v[202:205], v[24:27]
	v_mfma_f32_16x16x32_bf16 v[16:19], v[174:177], v[210:213], v[16:19]
	v_mfma_f32_16x16x32_bf16 v[8:11], v[182:185], v[210:213], v[8:11]
	v_mfma_f32_16x16x32_bf16 v[4:7], v[174:177], v[218:221], v[4:7]
	v_mfma_f32_16x16x32_bf16 v[0:3], v[182:185], v[218:221], v[0:3]
	s_setprio 0
	s_barrier
	s_add_i32 s50, s50, 2
	s_add_u32 s22, s22, 0x100
	s_addc_u32 s23, s23, 0
	s_add_u32 s48, s48, 0x100
	s_addc_u32 s49, s49, 0
	s_cmp_gt_u32 s50, 29
	s_cbranch_scc0 .LBB0_216
	s_and_b64 vcc, exec, s[10:11]
	s_cbranch_vccz .LBB0_219
	s_barrier

; #define PG8_STAGE(bufoff, gbase, voff) do { _Pragma("unroll") for (int _i = 0; _i < 2; ++_i) \
;         __builtin_amdgcn_global_load_lds((const unsigned*)((const char*)(gbase) + (voff)[_i]), (LAS unsigned*)(lds + (bufoff) + ldsw + _i * 8192), 16, 0, 0); } while (0)
; #define PG8_LDA(dst, b, h) do { _Pragma("unroll") for (int m = 0; m < 4; ++m) _Pragma("unroll") for (int k = 0; k < 2; ++k) dst[m][k] = *(const LAS bf16x8*)(lds + PG8_SA(b, h) + aoff + m * 2048 + k * 1024); } while (0)
; #define PG8_LDB(dst, b, h) do { _Pragma("unroll") for (int n = 0; n < 2; ++n) _Pragma("unroll") for (int k = 0; k < 2; ++k) dst[n][k] = *(const LAS bf16x8*)(lds + PG8_SB(b, h) + boff + n * 2048 + k * 1024); } while (0)
; #define PG8_MMA(ai, bj, At, Bt) do { __builtin_amdgcn_s_setprio(1); _Pragma("unroll") for (int m = 0; m < 4; ++m) _Pragma("unroll") for (int n = 0; n < 2; ++n) _Pragma("unroll") for (int k = 0; k < 2; ++k) \
;         acc[ai][bj][m][n] = __builtin_amdgcn_mfma_f32_16x16x32_bf16(Bt[n][k], At[m][k], acc[ai][bj][m][n], 0, 0, 0); __builtin_amdgcn_s_setprio(0); } while (0)
; #define PG8_WAIT_V(n) asm volatile("s_waitcnt vmcnt(" #n ")" ::: "memory")
; #define PG8_WAIT_L(n) asm volatile("s_waitcnt lgkmcnt(" #n ")" ::: "memory")
; #define PG8_BAR __builtin_amdgcn_s_barrier()
; #define PG8_SCHED __builtin_amdgcn_sched_barrier(0)
; template <class Epi, class Sched = StaticOrder, class EpiSub = NoSub, bool FAST = false>
; __device__ __forceinline__ void gemm_phase(LAS unsigned char* lds, const Gemm g, const Sched& S, const Epi& E, const EpiSub& ES = EpiSub()) {
;     ...
;             PG8_LDB(B0, 0, 0); PG8_LDB(B1, 0, 1); PG8_SCHED; PG8_LDA(At, 0, 0); PG8_STAGE(PG8_SA(1, 1), a1 + hstepA, voffA);
;             PG8_WAIT_V(8); PG8_WAIT_L(0); PG8_BAR; PG8_MMA(0, 0, At, B0); PG8_MMA(0, 1, At, B1); PG8_BAR; PG8_SCHED;
;             PG8_LDA(At, 0, 1); PG8_STAGE(PG8_SB(0, 0), b2, voffB); PG8_STAGE(PG8_SB(0, 1), b2 + hstepB, voffB); PG8_STAGE(PG8_SA(0, 0), a2, voffA);
.LBB0_600:
	ds_read_b128 v[100:103], v186
	ds_read_b128 v[112:115], v186 offset:1024
	ds_read_b128 v[124:127], v186 offset:2048
	ds_read_b128 v[136:139], v186 offset:3072
	ds_read_b128 v[144:147], v187
	ds_read_b128 v[148:151], v187 offset:1024
	ds_read_b128 v[152:155], v187 offset:2048
	ds_read_b128 v[170:173], v187 offset:3072
	s_add_i32 s51, s50, 2
	s_add_u32 s42, s40, 0xfffc0080
	s_addc_u32 s43, s41, -1
	s_cmp_eq_u32 s33, s50
	s_cselect_b32 s53, s1, s43
	s_cselect_b32 s52, s5, s42
	s_cselect_b32 s43, s7, s49
	s_cselect_b32 s42, s25, s48
	v_lshl_add_u64 v[190:191], s[40:41], 0, v[164:165]
	s_add_i32 m0, s55, 0xc000
	ds_read_b128 v[174:177], v188
	ds_read_b128 v[178:181], v188 offset:1024
	ds_read_b128 v[194:197], v188 offset:2048
	ds_read_b128 v[198:201], v188 offset:3072
	ds_read_b128 v[202:205], v188 offset:4096
	ds_read_b128 v[206:209], v188 offset:5120
	ds_read_b128 v[210:213], v188 offset:6144
	ds_read_b128 v[214:217], v188 offset:7168
	global_load_lds_dwordx4 v[190:191], off
	v_lshl_add_u64 v[190:191], s[40:41], 0, v[166:167]
	s_add_i32 m0, s55, 0xe000
	s_nop 0
	global_load_lds_dwordx4 v[190:191], off
	s_waitcnt vmcnt(8)
	s_waitcnt lgkmcnt(0)
	s_barrier
	s_setprio 1
	v_mfma_f32_16x16x32_bf16 v[140:143], v[100:103], v[174:177], v[140:143]
	v_mfma_f32_16x16x32_bf16 v[132:135], v[124:127], v[174:177], v[132:135]
	v_mfma_f32_16x16x32_bf16 v[116:119], v[100:103], v[194:197], v[116:119]
	v_mfma_f32_16x16x32_bf16 v[108:111], v[124:127], v[194:197], v[108:111]
	v_mfma_f32_16x16x32_bf16 v[92:95], v[100:103], v[202:205], v[92:95]
	v_mfma_f32_16x16x32_bf16 v[88:91], v[124:127], v[202:205], v[88:91]
	v_mfma_f32_16x16x32_bf16 v[76:79], v[100:103], v[210:213], v[76:79]
	v_mfma_f32_16x16x32_bf16 v[72:75], v[124:127], v[210:213], v[72:75]
	v_mfma_f32_16x16x32_bf16 v[140:143], v[112:115], v[178:181], v[140:143]
	v_mfma_f32_16x16x32_bf16 v[132:135], v[136:139], v[178:181], v[132:135]
	v_mfma_f32_16x16x32_bf16 v[116:119], v[112:115], v[198:201], v[116:119]
	v_mfma_f32_16x16x32_bf16 v[108:111], v[136:139], v[198:201], v[108:111]
	v_mfma_f32_16x16x32_bf16 v[92:95], v[112:115], v[206:209], v[92:95]
	v_mfma_f32_16x16x32_bf16 v[88:91], v[136:139], v[206:209], v[88:91]
	v_mfma_f32_16x16x32_bf16 v[76:79], v[112:115], v[214:217], v[76:79]
	v_mfma_f32_16x16x32_bf16 v[72:75], v[136:139], v[214:217], v[72:75]
	s_setprio 0
	s_setprio 1
	v_mfma_f32_16x16x32_bf16 v[128:131], v[144:147], v[174:177], v[128:131]
	v_mfma_f32_16x16x32_bf16 v[120:123], v[152:155], v[174:177], v[120:123]
	v_mfma_f32_16x16x32_bf16 v[104:107], v[144:147], v[194:197], v[104:107]
	v_mfma_f32_16x16x32_bf16 v[96:99], v[152:155], v[194:197], v[96:99]
	v_mfma_f32_16x16x32_bf16 v[84:87], v[144:147], v[202:205], v[84:87]
	v_mfma_f32_16x16x32_bf16 v[80:83], v[152:155], v[202:205], v[80:83]
	v_mfma_f32_16x16x32_bf16 v[68:71], v[144:147], v[210:213], v[68:71]
	v_mfma_f32_16x16x32_bf16 v[64:67], v[152:155], v[210:213], v[64:67]
	v_mfma_f32_16x16x32_bf16 v[128:131], v[148:151], v[178:181], v[128:131]
	v_mfma_f32_16x16x32_bf16 v[120:123], v[170:173], v[178:181], v[120:123]
	v_mfma_f32_16x16x32_bf16 v[104:107], v[148:151], v[198:201], v[104:107]
	v_mfma_f32_16x16x32_bf16 v[96:99], v[170:173], v[198:201], v[96:99]
	v_mfma_f32_16x16x32_bf16 v[84:87], v[148:151], v[206:209], v[84:87]
	v_mfma_f32_16x16x32_bf16 v[80:83], v[170:173], v[206:209], v[80:83]
	v_mfma_f32_16x16x32_bf16 v[68:71], v[148:151], v[214:217], v[68:71]
	v_mfma_f32_16x16x32_bf16 v[64:67], v[170:173], v[214:217], v[64:67]
	s_setprio 0
	s_barrier
	s_add_i32 s50, s75, s54
	v_lshl_add_u64 v[190:191], s[42:43], 0, v[158:159]
	s_mov_b32 m0, s50
	ds_read_b128 v[174:177], v188 offset:16384
	ds_read_b128 v[178:181], v188 offset:17408
	ds_read_b128 v[194:197], v188 offset:18432
	ds_read_b128 v[198:201], v188 offset:19456
	ds_read_b128 v[202:205], v188 offset:20480
	ds_read_b128 v[206:209], v188 offset:21504
	ds_read_b128 v[210:213], v188 offset:22528
	ds_read_b128 v[214:217], v188 offset:23552
	global_load_lds_dwordx4 v[190:191], off
	s_add_i32 m0, s50, 0x2000
	s_add_u32 s70, s42, 0x40000
	v_lshl_add_u64 v[218:219], s[42:43], 0, v[162:163]
	s_addc_u32 s71, s43, 0
	s_add_i32 s50, s80, s54
	global_load_lds_dwordx4 v[218:219], off
	v_lshl_add_u64 v[220:221], s[70:71], 0, v[158:159]
	s_mov_b32 m0, s50
	v_lshl_add_u64 v[222:223], s[52:53], 0, v[160:161]
	global_load_lds_dwordx4 v[220:221], off
	v_lshl_add_u64 v[220:221], s[70:71], 0, v[162:163]
	s_add_i32 m0, s50, 0x2000
	s_nop 0
	global_load_lds_dwordx4 v[220:221], off
	v_lshl_add_u64 v[220:221], s[52:53], 0, v[156:157]
	s_mov_b32 m0, s55
	s_nop 0
	global_load_lds_dwordx4 v[220:221], off
	s_mov_b32 m0, s56
	s_nop 0
	global_load_lds_dwordx4 v[222:223], off
	s_waitcnt vmcnt(8)
	s_waitcnt lgkmcnt(0)
	s_barrier
; #define PG8_STAGE(bufoff, gbase, voff) do { _Pragma("unroll") for (int _i = 0; _i < 2; ++_i) \
;         __builtin_amdgcn_global_load_lds((const unsigned*)((const char*)(gbase) + (voff)[_i]), (LAS unsigned*)(lds + (bufoff) + ldsw + _i * 8192), 16, 0, 0); } while (0)
; #define PG8_LDA(dst, b, h) do { _Pragma("unroll") for (int m = 0; m < 4; ++m) _Pragma("unroll") for (int k = 0; k < 2; ++k) dst[m][k] = *(const LAS bf16x8*)(lds + PG8_SA(b, h) + aoff + m * 2048 + k * 1024); } while (0)
; #define PG8_LDB(dst, b, h) do { _Pragma("unroll") for (int n = 0; n < 2; ++n) _Pragma("unroll") for (int k = 0; k < 2; ++k) dst[n][k] = *(const LAS bf16x8*)(lds + PG8_SB(b, h) + boff + n * 2048 + k * 1024); } while (0)
; #define PG8_MMA(ai, bj, At, Bt) do { __builtin_amdgcn_s_setprio(1); _Pragma("unroll") for (int m = 0; m < 4; ++m) _Pragma("unroll") for (int n = 0; n < 2; ++n) _Pragma("unroll") for (int k = 0; k < 2; ++k) \
;         acc[ai][bj][m][n] = __builtin_amdgcn_mfma_f32_16x16x32_bf16(Bt[n][k], At[m][k], acc[ai][bj][m][n], 0, 0, 0); __builtin_amdgcn_s_setprio(0); } while (0)
; #define PG8_WAIT_V(n) asm volatile("s_waitcnt vmcnt(" #n ")" ::: "memory")
; #define PG8_WAIT_L(n) asm volatile("s_waitcnt lgkmcnt(" #n ")" ::: "memory")
; #define PG8_BAR __builtin_amdgcn_s_barrier()
; #define PG8_SCHED __builtin_amdgcn_sched_barrier(0)
; template <class Epi, class Sched = StaticOrder, class EpiSub = NoSub, bool FAST = false>
; __device__ __forceinline__ void gemm_phase(LAS unsigned char* lds, const Gemm g, const Sched& S, const Epi& E, const EpiSub& ES = EpiSub()) {
;     ...
;             PG8_WAIT_V(8); PG8_WAIT_L(0); PG8_BAR; PG8_MMA(1, 0, At, B0); PG8_MMA(1, 1, At, B1); PG8_BAR; PG8_SCHED;
;             PG8_LDB(B0, 1, 0); PG8_LDB(B1, 1, 1); PG8_SCHED; PG8_LDA(At, 1, 0); PG8_STAGE(PG8_SA(0, 1), a2 + hstepA, voffA);
;             PG8_WAIT_V(8); PG8_WAIT_L(0); PG8_BAR; PG8_MMA(0, 0, At, B0); PG8_MMA(0, 1, At, B1); PG8_BAR; PG8_SCHED;
	s_setprio 1
	v_mfma_f32_16x16x32_bf16 v[60:63], v[100:103], v[174:177], v[60:63]
	v_mfma_f32_16x16x32_bf16 v[56:59], v[124:127], v[174:177], v[56:59]
	v_mfma_f32_16x16x32_bf16 v[44:47], v[100:103], v[194:197], v[44:47]
	v_mfma_f32_16x16x32_bf16 v[40:43], v[124:127], v[194:197], v[40:43]
	v_mfma_f32_16x16x32_bf16 v[28:31], v[100:103], v[202:205], v[28:31]
	v_mfma_f32_16x16x32_bf16 v[24:27], v[124:127], v[202:205], v[24:27]
	v_mfma_f32_16x16x32_bf16 v[12:15], v[100:103], v[210:213], v[12:15]
	v_mfma_f32_16x16x32_bf16 v[8:11], v[124:127], v[210:213], v[8:11]
	v_mfma_f32_16x16x32_bf16 v[60:63], v[112:115], v[178:181], v[60:63]
	v_mfma_f32_16x16x32_bf16 v[56:59], v[136:139], v[178:181], v[56:59]
	v_mfma_f32_16x16x32_bf16 v[44:47], v[112:115], v[198:201], v[44:47]
	v_mfma_f32_16x16x32_bf16 v[40:43], v[136:139], v[198:201], v[40:43]
	v_mfma_f32_16x16x32_bf16 v[28:31], v[112:115], v[206:209], v[28:31]
	v_mfma_f32_16x16x32_bf16 v[24:27], v[136:139], v[206:209], v[24:27]
	v_mfma_f32_16x16x32_bf16 v[12:15], v[112:115], v[214:217], v[12:15]
	v_mfma_f32_16x16x32_bf16 v[8:11], v[136:139], v[214:217], v[8:11]
	s_setprio 0
	s_setprio 1
	v_mfma_f32_16x16x32_bf16 v[52:55], v[144:147], v[174:177], v[52:55]
	v_mfma_f32_16x16x32_bf16 v[48:51], v[152:155], v[174:177], v[48:51]
	v_mfma_f32_16x16x32_bf16 v[36:39], v[144:147], v[194:197], v[36:39]
	v_mfma_f32_16x16x32_bf16 v[32:35], v[152:155], v[194:197], v[32:35]
	v_mfma_f32_16x16x32_bf16 v[20:23], v[144:147], v[202:205], v[20:23]
	v_mfma_f32_16x16x32_bf16 v[16:19], v[152:155], v[202:205], v[16:19]
	v_mfma_f32_16x16x32_bf16 v[4:7], v[144:147], v[210:213], v[4:7]
	v_mfma_f32_16x16x32_bf16 v[0:3], v[152:155], v[210:213], v[0:3]
	v_mfma_f32_16x16x32_bf16 v[52:55], v[148:151], v[178:181], v[52:55]
	v_mfma_f32_16x16x32_bf16 v[48:51], v[170:173], v[178:181], v[48:51]
	v_mfma_f32_16x16x32_bf16 v[36:39], v[148:151], v[198:201], v[36:39]
	v_mfma_f32_16x16x32_bf16 v[32:35], v[170:173], v[198:201], v[32:35]
	v_mfma_f32_16x16x32_bf16 v[20:23], v[148:151], v[206:209], v[20:23]
	v_mfma_f32_16x16x32_bf16 v[16:19], v[170:173], v[206:209], v[16:19]
	v_mfma_f32_16x16x32_bf16 v[4:7], v[148:151], v[214:217], v[4:7]
	v_mfma_f32_16x16x32_bf16 v[0:3], v[170:173], v[214:217], v[0:3]
	s_setprio 0
	s_barrier
	s_add_i32 s50, 0, 0x18000
	s_add_i32 s70, 0, 0x1c000
	v_add_u32_e32 v136, s50, v183
	v_add_u32_e32 v170, s70, v183
	ds_read_b128 v[100:103], v136
	ds_read_b128 v[112:115], v136 offset:1024
	ds_read_b128 v[124:127], v136 offset:2048
	ds_read_b128 v[136:139], v136 offset:3072
	ds_read_b128 v[144:147], v170
	ds_read_b128 v[148:151], v170 offset:1024
	ds_read_b128 v[152:155], v170 offset:2048
	ds_read_b128 v[170:173], v170 offset:3072
	s_add_u32 s52, s52, 0x40000
	s_addc_u32 s53, s53, 0
	s_mov_b32 m0, s57
	v_lshl_add_u64 v[224:225], s[52:53], 0, v[156:157]
	ds_read_b128 v[174:177], v188 offset:32768
	ds_read_b128 v[178:181], v188 offset:33792
	ds_read_b128 v[194:197], v188 offset:34816
	ds_read_b128 v[198:201], v188 offset:35840
	ds_read_b128 v[202:205], v188 offset:36864
	ds_read_b128 v[206:209], v188 offset:37888
	ds_read_b128 v[210:213], v188 offset:38912
	ds_read_b128 v[214:217], v188 offset:39936
	global_load_lds_dwordx4 v[224:225], off
	v_lshl_add_u64 v[224:225], s[52:53], 0, v[160:161]
	s_mov_b32 m0, s58
	s_nop 0
	global_load_lds_dwordx4 v[224:225], off
	s_waitcnt vmcnt(8)
	s_waitcnt lgkmcnt(0)
	s_barrier
	s_setprio 1
	v_mfma_f32_16x16x32_bf16 v[140:143], v[100:103], v[174:177], v[140:143]
	v_mfma_f32_16x16x32_bf16 v[132:135], v[124:127], v[174:177], v[132:135]
	v_mfma_f32_16x16x32_bf16 v[116:119], v[100:103], v[194:197], v[116:119]
	v_mfma_f32_16x16x32_bf16 v[108:111], v[124:127], v[194:197], v[108:111]
	v_mfma_f32_16x16x32_bf16 v[92:95], v[100:103], v[202:205], v[92:95]
	v_mfma_f32_16x16x32_bf16 v[88:91], v[124:127], v[202:205], v[88:91]
	v_mfma_f32_16x16x32_bf16 v[76:79], v[100:103], v[210:213], v[76:79]
	v_mfma_f32_16x16x32_bf16 v[72:75], v[124:127], v[210:213], v[72:75]
	v_mfma_f32_16x16x32_bf16 v[140:143], v[112:115], v[178:181], v[140:143]
	v_mfma_f32_16x16x32_bf16 v[132:135], v[136:139], v[178:181], v[132:135]
	v_mfma_f32_16x16x32_bf16 v[116:119], v[112:115], v[198:201], v[116:119]
	v_mfma_f32_16x16x32_bf16 v[108:111], v[136:139], v[198:201], v[108:111]
	v_mfma_f32_16x16x32_bf16 v[92:95], v[112:115], v[206:209], v[92:95]
	v_mfma_f32_16x16x32_bf16 v[88:91], v[136:139], v[206:209], v[88:91]
	v_mfma_f32_16x16x32_bf16 v[76:79], v[112:115], v[214:217], v[76:79]
	v_mfma_f32_16x16x32_bf16 v[72:75], v[136:139], v[214:217], v[72:75]
	s_setprio 0
	s_setprio 1
	v_mfma_f32_16x16x32_bf16 v[128:131], v[144:147], v[174:177], v[128:131]
	v_mfma_f32_16x16x32_bf16 v[120:123], v[152:155], v[174:177], v[120:123]
	v_mfma_f32_16x16x32_bf16 v[104:107], v[144:147], v[194:197], v[104:107]
	v_mfma_f32_16x16x32_bf16 v[96:99], v[152:155], v[194:197], v[96:99]
	v_mfma_f32_16x16x32_bf16 v[84:87], v[144:147], v[202:205], v[84:87]
	v_mfma_f32_16x16x32_bf16 v[80:83], v[152:155], v[202:205], v[80:83]
	v_mfma_f32_16x16x32_bf16 v[68:71], v[144:147], v[210:213], v[68:71]
	v_mfma_f32_16x16x32_bf16 v[64:67], v[152:155], v[210:213], v[64:67]
	v_mfma_f32_16x16x32_bf16 v[128:131], v[148:151], v[178:181], v[128:131]
	v_mfma_f32_16x16x32_bf16 v[120:123], v[170:173], v[178:181], v[120:123]
	v_mfma_f32_16x16x32_bf16 v[104:107], v[148:151], v[198:201], v[104:107]
	v_mfma_f32_16x16x32_bf16 v[96:99], v[170:173], v[198:201], v[96:99]
	v_mfma_f32_16x16x32_bf16 v[84:87], v[148:151], v[206:209], v[84:87]
	v_mfma_f32_16x16x32_bf16 v[80:83], v[170:173], v[206:209], v[80:83]
	v_mfma_f32_16x16x32_bf16 v[68:71], v[148:151], v[214:217], v[68:71]
	v_mfma_f32_16x16x32_bf16 v[64:67], v[170:173], v[214:217], v[64:67]
	s_setprio 0
	s_barrier
; #define PG8_STAGE(bufoff, gbase, voff) do { _Pragma("unroll") for (int _i = 0; _i < 2; ++_i) \
;         __builtin_amdgcn_global_load_lds((const unsigned*)((const char*)(gbase) + (voff)[_i]), (LAS unsigned*)(lds + (bufoff) + ldsw + _i * 8192), 16, 0, 0); } while (0)
; #define PG8_LDA(dst, b, h) do { _Pragma("unroll") for (int m = 0; m < 4; ++m) _Pragma("unroll") for (int k = 0; k < 2; ++k) dst[m][k] = *(const LAS bf16x8*)(lds + PG8_SA(b, h) + aoff + m * 2048 + k * 1024); } while (0)
; #define PG8_MMA(ai, bj, At, Bt) do { __builtin_amdgcn_s_setprio(1); _Pragma("unroll") for (int m = 0; m < 4; ++m) _Pragma("unroll") for (int n = 0; n < 2; ++n) _Pragma("unroll") for (int k = 0; k < 2; ++k) \
;         acc[ai][bj][m][n] = __builtin_amdgcn_mfma_f32_16x16x32_bf16(Bt[n][k], At[m][k], acc[ai][bj][m][n], 0, 0, 0); __builtin_amdgcn_s_setprio(0); } while (0)
; #define PG8_WAIT_V(n) asm volatile("s_waitcnt vmcnt(" #n ")" ::: "memory")
; #define PG8_WAIT_L(n) asm volatile("s_waitcnt lgkmcnt(" #n ")" ::: "memory")
; #define PG8_BAR __builtin_amdgcn_s_barrier()
; #define PG8_SCHED __builtin_amdgcn_sched_barrier(0)
; template <class Epi, class Sched = StaticOrder, class EpiSub = NoSub, bool FAST = false>
; __device__ __forceinline__ void gemm_phase(LAS unsigned char* lds, const Gemm g, const Sched& S, const Epi& E, const EpiSub& ES = EpiSub()) {
;     ...
;             PG8_LDA(At, 1, 1); PG8_STAGE(PG8_SB(1, 0), b3, voffB); PG8_STAGE(PG8_SB(1, 1), b3 + hstepB, voffB); PG8_STAGE(PG8_SA(1, 0), a3, voffA);
;             PG8_WAIT_V(8); PG8_WAIT_L(0); PG8_BAR; PG8_MMA(1, 0, At, B0); PG8_MMA(1, 1, At, B1); PG8_BAR; PG8_SCHED;
;     ...
;         if constexpr (FAST && PG8_ALIGN) { if (wr == 0) PG8_BAR; }
	s_add_i32 s50, s50, s54
	v_lshl_add_u64 v[190:191], v[190:191], 0, s[12:13]
	s_mov_b32 m0, s50
	ds_read_b128 v[174:177], v188 offset:49152
	ds_read_b128 v[178:181], v188 offset:50176
	ds_read_b128 v[194:197], v188 offset:51200
	ds_read_b128 v[198:201], v188 offset:52224
	ds_read_b128 v[202:205], v188 offset:53248
	ds_read_b128 v[206:209], v188 offset:54272
	ds_read_b128 v[210:213], v188 offset:55296
	ds_read_b128 v[214:217], v188 offset:56320
	global_load_lds_dwordx4 v[190:191], off
	s_add_i32 m0, s50, 0x2000
	s_add_u32 s42, s42, 0x40080
	v_lshl_add_u64 v[190:191], v[218:219], 0, s[12:13]
	s_addc_u32 s43, s43, 0
	s_add_i32 s50, s70, s54
	global_load_lds_dwordx4 v[190:191], off
	v_lshl_add_u64 v[190:191], s[42:43], 0, v[158:159]
	s_mov_b32 m0, s50
	s_nop 0
	global_load_lds_dwordx4 v[190:191], off
	v_lshl_add_u64 v[190:191], s[42:43], 0, v[162:163]
	s_add_i32 m0, s50, 0x2000
	s_nop 0
	global_load_lds_dwordx4 v[190:191], off
	v_lshl_add_u64 v[190:191], v[220:221], 0, s[12:13]
	s_mov_b32 m0, s69
	s_nop 0
	global_load_lds_dwordx4 v[190:191], off
	v_lshl_add_u64 v[190:191], v[222:223], 0, s[12:13]
	s_mov_b32 m0, s74
	s_nop 0
	global_load_lds_dwordx4 v[190:191], off
	s_waitcnt vmcnt(8)
	s_waitcnt lgkmcnt(0)
	s_barrier
	s_setprio 1
	v_mfma_f32_16x16x32_bf16 v[60:63], v[100:103], v[174:177], v[60:63]
	v_mfma_f32_16x16x32_bf16 v[56:59], v[124:127], v[174:177], v[56:59]
	v_mfma_f32_16x16x32_bf16 v[44:47], v[100:103], v[194:197], v[44:47]
	v_mfma_f32_16x16x32_bf16 v[40:43], v[124:127], v[194:197], v[40:43]
	v_mfma_f32_16x16x32_bf16 v[28:31], v[100:103], v[202:205], v[28:31]
	v_mfma_f32_16x16x32_bf16 v[24:27], v[124:127], v[202:205], v[24:27]
	v_mfma_f32_16x16x32_bf16 v[12:15], v[100:103], v[210:213], v[12:15]
	v_mfma_f32_16x16x32_bf16 v[8:11], v[124:127], v[210:213], v[8:11]
	v_mfma_f32_16x16x32_bf16 v[60:63], v[112:115], v[178:181], v[60:63]
	v_mfma_f32_16x16x32_bf16 v[56:59], v[136:139], v[178:181], v[56:59]
	v_mfma_f32_16x16x32_bf16 v[44:47], v[112:115], v[198:201], v[44:47]
	v_mfma_f32_16x16x32_bf16 v[40:43], v[136:139], v[198:201], v[40:43]
	v_mfma_f32_16x16x32_bf16 v[28:31], v[112:115], v[206:209], v[28:31]
	v_mfma_f32_16x16x32_bf16 v[24:27], v[136:139], v[206:209], v[24:27]
	v_mfma_f32_16x16x32_bf16 v[12:15], v[112:115], v[214:217], v[12:15]
	v_mfma_f32_16x16x32_bf16 v[8:11], v[136:139], v[214:217], v[8:11]
	s_setprio 0
	s_setprio 1
	v_mfma_f32_16x16x32_bf16 v[52:55], v[144:147], v[174:177], v[52:55]
	v_mfma_f32_16x16x32_bf16 v[48:51], v[152:155], v[174:177], v[48:51]
	v_mfma_f32_16x16x32_bf16 v[36:39], v[144:147], v[194:197], v[36:39]
	v_mfma_f32_16x16x32_bf16 v[32:35], v[152:155], v[194:197], v[32:35]
	v_mfma_f32_16x16x32_bf16 v[20:23], v[144:147], v[202:205], v[20:23]
	v_mfma_f32_16x16x32_bf16 v[16:19], v[152:155], v[202:205], v[16:19]
	v_mfma_f32_16x16x32_bf16 v[4:7], v[144:147], v[210:213], v[4:7]
	v_mfma_f32_16x16x32_bf16 v[0:3], v[152:155], v[210:213], v[0:3]
	v_mfma_f32_16x16x32_bf16 v[52:55], v[148:151], v[178:181], v[52:55]
	v_mfma_f32_16x16x32_bf16 v[48:51], v[170:173], v[178:181], v[48:51]
	v_mfma_f32_16x16x32_bf16 v[36:39], v[148:151], v[198:201], v[36:39]
	v_mfma_f32_16x16x32_bf16 v[32:35], v[170:173], v[198:201], v[32:35]
	v_mfma_f32_16x16x32_bf16 v[20:23], v[148:151], v[206:209], v[20:23]
	v_mfma_f32_16x16x32_bf16 v[16:19], v[170:173], v[206:209], v[16:19]
	v_mfma_f32_16x16x32_bf16 v[4:7], v[148:151], v[214:217], v[4:7]
	v_mfma_f32_16x16x32_bf16 v[0:3], v[170:173], v[214:217], v[0:3]
	s_setprio 0
	s_barrier
	s_add_u32 s40, s40, 0x100
	s_addc_u32 s41, s41, 0
	s_add_u32 s48, s48, 0x100
	s_addc_u32 s49, s49, 0
	s_cmp_ge_u32 s51, s27
	s_mov_b32 s50, s51
	s_cbranch_scc0 .LBB0_600
	s_and_b64 vcc, exec, s[14:15]
	s_cbranch_vccz .LBB0_603
	s_barrier

; #define PG8_STAGE(bufoff, gbase, voff) do { _Pragma("unroll") for (int _i = 0; _i < 2; ++_i) \
;         __builtin_amdgcn_global_load_lds((const unsigned*)((const char*)(gbase) + (voff)[_i]), (LAS unsigned*)(lds + (bufoff) + ldsw + _i * 8192), 16, 0, 0); } while (0)
; #define PG8_LDA(dst, b, h) do { _Pragma("unroll") for (int m = 0; m < 4; ++m) _Pragma("unroll") for (int k = 0; k < 2; ++k) dst[m][k] = *(const LAS bf16x8*)(lds + PG8_SA(b, h) + aoff + m * 2048 + k * 1024); } while (0)
; #define PG8_LDB(dst, b, h) do { _Pragma("unroll") for (int n = 0; n < 2; ++n) _Pragma("unroll") for (int k = 0; k < 2; ++k) dst[n][k] = *(const LAS bf16x8*)(lds + PG8_SB(b, h) + boff + n * 2048 + k * 1024); } while (0)
; #define PG8_WAIT_V(n) asm volatile("s_waitcnt vmcnt(" #n ")" ::: "memory")
; #define PG8_BAR __builtin_amdgcn_s_barrier()
; template <class Epi, class Sched = StaticOrder, class EpiSub = NoSub, bool FAST = false>
; __device__ __forceinline__ void gemm_phase(LAS unsigned char* lds, const Gemm g, const Sched& S, const Epi& E, const EpiSub& ES = EpiSub()) {
;     ...
;         const bool has_next = S.next(ui + 1, nxt);
;         const size_t nko = (has_next && nxt.kb >= 0) ? nxt.kb * ksubB : 0;
;         const char* nA = has_next ? (const char*)g.A + (size_t)nxt.pm * tstepA + (size_t)nxt.pn * g.acs + nko : cA; const char* nB = has_next ? (const char*)g.Bt + (size_t)nxt.pn * tstepB + nko : cB;
;         const int nt = cur.kb < 0 ? ntMain : ntSub;
;         for (int t = 0; t < nt; t += 2) {
;             const bool last = (t == nt - 2);
;             const char* a1 = cA + (size_t)(t + 1) * kstep;
;             const char* a2 = last ? nA : cA + (size_t)(t + 2) * kstep; const char* b2 = last ? nB : cB + (size_t)(t + 2) * kstep;
;             const char* a3 = a2 + kstep; const char* b3 = b2 + kstep;
;             if constexpr (FAST && PG8_SP2) {
;             PG8_LDB(B0, 0, 0); PG8_LDB(B1, 0, 1); PG8_SCHED; PG8_LDA(At, 0, 0); PG8_STAGE(PG8_SA(1, 1), a1 + hstepA, voffA);
;             PG8_WAIT_V(8); PG8_WAIT_L(0); PG8_BAR; PG8_MMA(0, 0, At, B0); PG8_MMA(0, 1, At, B1); PG8_BAR; PG8_SCHED;
;             PG8_LDA(At, 0, 1); PG8_STAGE(PG8_SB(0, 0), b2, voffB); PG8_STAGE(PG8_SB(0, 1), b2 + hstepB, voffB); PG8_STAGE(PG8_SA(0, 0), a2, voffA);
;             PG8_WAIT_V(8); PG8_WAIT_L(0); PG8_BAR; PG8_MMA(1, 0, At, B0); PG8_MMA(1, 1, At, B1); PG8_BAR; PG8_SCHED;
.LBB0_632:
	ds_read_b128 v[104:107], v224
	ds_read_b128 v[108:111], v224 offset:1024
	ds_read_b128 v[120:123], v224 offset:2048
	ds_read_b128 v[124:127], v224 offset:3072
	ds_read_b128 v[136:139], v225
	ds_read_b128 v[140:143], v225 offset:1024
	ds_read_b128 v[152:155], v225 offset:2048
	ds_read_b128 v[156:159], v225 offset:3072
	s_add_i32 s50, s42, 2
	s_add_u32 s40, s38, 0xfff80080
	s_addc_u32 s41, s39, -1
	s_cmp_eq_u32 s33, s42
	s_cselect_b32 s42, s5, s40
	s_cselect_b32 s43, s1, s41
	s_cselect_b32 s41, s21, s49
	s_cselect_b32 s40, s23, s48
	v_lshl_add_u64 v[208:209], s[38:39], 0, v[202:203]
	s_add_i32 m0, s53, 0xc000
	ds_read_b128 v[160:163], v226
	ds_read_b128 v[164:167], v226 offset:1024
	ds_read_b128 v[168:171], v226 offset:2048
	ds_read_b128 v[172:175], v226 offset:3072
	ds_read_b128 v[176:179], v226 offset:4096
	ds_read_b128 v[180:183], v226 offset:5120
	ds_read_b128 v[184:187], v226 offset:6144
	ds_read_b128 v[188:191], v226 offset:7168
	global_load_lds_dwordx4 v[208:209], off
	v_lshl_add_u64 v[208:209], s[38:39], 0, v[204:205]
	s_add_i32 m0, s53, 0xe000
	s_nop 0
	global_load_lds_dwordx4 v[208:209], off
	s_waitcnt vmcnt(8)
	s_waitcnt lgkmcnt(0)
	s_barrier
	s_setprio 1
	v_mfma_f32_16x16x32_bf16 v[148:151], v[104:107], v[160:163], v[148:151]
	v_mfma_f32_16x16x32_bf16 v[144:147], v[120:123], v[160:163], v[144:147]
	v_mfma_f32_16x16x32_bf16 v[116:119], v[104:107], v[168:171], v[116:119]
	v_mfma_f32_16x16x32_bf16 v[112:115], v[120:123], v[168:171], v[112:115]
	v_mfma_f32_16x16x32_bf16 v[92:95], v[104:107], v[176:179], v[92:95]
	v_mfma_f32_16x16x32_bf16 v[88:91], v[120:123], v[176:179], v[88:91]
	v_mfma_f32_16x16x32_bf16 v[76:79], v[104:107], v[184:187], v[76:79]
	v_mfma_f32_16x16x32_bf16 v[72:75], v[120:123], v[184:187], v[72:75]
	v_mfma_f32_16x16x32_bf16 v[148:151], v[108:111], v[164:167], v[148:151]
	v_mfma_f32_16x16x32_bf16 v[144:147], v[124:127], v[164:167], v[144:147]
	v_mfma_f32_16x16x32_bf16 v[116:119], v[108:111], v[172:175], v[116:119]
	v_mfma_f32_16x16x32_bf16 v[112:115], v[124:127], v[172:175], v[112:115]
	v_mfma_f32_16x16x32_bf16 v[92:95], v[108:111], v[180:183], v[92:95]
	v_mfma_f32_16x16x32_bf16 v[88:91], v[124:127], v[180:183], v[88:91]
	v_mfma_f32_16x16x32_bf16 v[76:79], v[108:111], v[188:191], v[76:79]
	v_mfma_f32_16x16x32_bf16 v[72:75], v[124:127], v[188:191], v[72:75]
	s_setprio 0
	s_setprio 1
	v_mfma_f32_16x16x32_bf16 v[132:135], v[136:139], v[160:163], v[132:135]
	v_mfma_f32_16x16x32_bf16 v[128:131], v[152:155], v[160:163], v[128:131]
	v_mfma_f32_16x16x32_bf16 v[100:103], v[136:139], v[168:171], v[100:103]
	v_mfma_f32_16x16x32_bf16 v[96:99], v[152:155], v[168:171], v[96:99]
	v_mfma_f32_16x16x32_bf16 v[84:87], v[136:139], v[176:179], v[84:87]
	v_mfma_f32_16x16x32_bf16 v[80:83], v[152:155], v[176:179], v[80:83]
	v_mfma_f32_16x16x32_bf16 v[68:71], v[136:139], v[184:187], v[68:71]
	v_mfma_f32_16x16x32_bf16 v[64:67], v[152:155], v[184:187], v[64:67]
	v_mfma_f32_16x16x32_bf16 v[132:135], v[140:143], v[164:167], v[132:135]
	v_mfma_f32_16x16x32_bf16 v[128:131], v[156:159], v[164:167], v[128:131]
	v_mfma_f32_16x16x32_bf16 v[100:103], v[140:143], v[172:175], v[100:103]
	v_mfma_f32_16x16x32_bf16 v[96:99], v[156:159], v[172:175], v[96:99]
	v_mfma_f32_16x16x32_bf16 v[84:87], v[140:143], v[180:183], v[84:87]
	v_mfma_f32_16x16x32_bf16 v[80:83], v[156:159], v[180:183], v[80:83]
	v_mfma_f32_16x16x32_bf16 v[68:71], v[140:143], v[188:191], v[68:71]
	v_mfma_f32_16x16x32_bf16 v[64:67], v[156:159], v[188:191], v[64:67]
	s_setprio 0
	s_barrier
	s_add_i32 s51, s75, s52
	v_lshl_add_u64 v[208:209], s[40:41], 0, v[196:197]
	s_mov_b32 m0, s51
	ds_read_b128 v[160:163], v226 offset:16384
	ds_read_b128 v[164:167], v226 offset:17408
	ds_read_b128 v[168:171], v226 offset:18432
	ds_read_b128 v[172:175], v226 offset:19456
	ds_read_b128 v[176:179], v226 offset:20480
	ds_read_b128 v[180:183], v226 offset:21504
	ds_read_b128 v[184:187], v226 offset:22528
	ds_read_b128 v[188:191], v226 offset:23552
	global_load_lds_dwordx4 v[208:209], off
	s_add_i32 m0, s51, 0x2000
	s_add_u32 s70, s40, 0x80000
	v_lshl_add_u64 v[210:211], s[40:41], 0, v[200:201]
	s_addc_u32 s71, s41, 0
	s_add_i32 s51, s78, s52
	global_load_lds_dwordx4 v[210:211], off
	v_lshl_add_u64 v[212:213], s[70:71], 0, v[196:197]
	s_mov_b32 m0, s51
	v_lshl_add_u64 v[214:215], s[42:43], 0, v[198:199]
	global_load_lds_dwordx4 v[212:213], off
	v_lshl_add_u64 v[212:213], s[70:71], 0, v[200:201]
	s_add_i32 m0, s51, 0x2000
	s_nop 0
	global_load_lds_dwordx4 v[212:213], off
	v_lshl_add_u64 v[212:213], s[42:43], 0, v[194:195]
	s_mov_b32 m0, s53
	s_nop 0
	global_load_lds_dwordx4 v[212:213], off
	s_mov_b32 m0, s54
	s_nop 0
	global_load_lds_dwordx4 v[214:215], off
	s_waitcnt vmcnt(8)
	s_waitcnt lgkmcnt(0)
	s_barrier
; #define PG8_STAGE(bufoff, gbase, voff) do { _Pragma("unroll") for (int _i = 0; _i < 2; ++_i) \
;         __builtin_amdgcn_global_load_lds((const unsigned*)((const char*)(gbase) + (voff)[_i]), (LAS unsigned*)(lds + (bufoff) + ldsw + _i * 8192), 16, 0, 0); } while (0)
; #define PG8_LDA(dst, b, h) do { _Pragma("unroll") for (int m = 0; m < 4; ++m) _Pragma("unroll") for (int k = 0; k < 2; ++k) dst[m][k] = *(const LAS bf16x8*)(lds + PG8_SA(b, h) + aoff + m * 2048 + k * 1024); } while (0)
; #define PG8_LDB(dst, b, h) do { _Pragma("unroll") for (int n = 0; n < 2; ++n) _Pragma("unroll") for (int k = 0; k < 2; ++k) dst[n][k] = *(const LAS bf16x8*)(lds + PG8_SB(b, h) + boff + n * 2048 + k * 1024); } while (0)
; #define PG8_MMA(ai, bj, At, Bt) do { __builtin_amdgcn_s_setprio(1); _Pragma("unroll") for (int m = 0; m < 4; ++m) _Pragma("unroll") for (int n = 0; n < 2; ++n) _Pragma("unroll") for (int k = 0; k < 2; ++k) \
;         acc[ai][bj][m][n] = __builtin_amdgcn_mfma_f32_16x16x32_bf16(Bt[n][k], At[m][k], acc[ai][bj][m][n], 0, 0, 0); __builtin_amdgcn_s_setprio(0); } while (0)
; #define PG8_WAIT_V(n) asm volatile("s_waitcnt vmcnt(" #n ")" ::: "memory")
; #define PG8_WAIT_L(n) asm volatile("s_waitcnt lgkmcnt(" #n ")" ::: "memory")
; #define PG8_BAR __builtin_amdgcn_s_barrier()
; #define PG8_SCHED __builtin_amdgcn_sched_barrier(0)
; template <class Epi, class Sched = StaticOrder, class EpiSub = NoSub, bool FAST = false>
; __device__ __forceinline__ void gemm_phase(LAS unsigned char* lds, const Gemm g, const Sched& S, const Epi& E, const EpiSub& ES = EpiSub()) {
;     ...
;             PG8_WAIT_V(8); PG8_WAIT_L(0); PG8_BAR; PG8_MMA(1, 0, At, B0); PG8_MMA(1, 1, At, B1); PG8_BAR; PG8_SCHED;
;             PG8_LDB(B0, 1, 0); PG8_LDB(B1, 1, 1); PG8_SCHED; PG8_LDA(At, 1, 0); PG8_STAGE(PG8_SA(0, 1), a2 + hstepA, voffA);
;             PG8_WAIT_V(8); PG8_WAIT_L(0); PG8_BAR; PG8_MMA(0, 0, At, B0); PG8_MMA(0, 1, At, B1); PG8_BAR; PG8_SCHED;
	s_setprio 1
	v_mfma_f32_16x16x32_bf16 v[60:63], v[104:107], v[160:163], v[60:63]
	v_mfma_f32_16x16x32_bf16 v[56:59], v[120:123], v[160:163], v[56:59]
	v_mfma_f32_16x16x32_bf16 v[44:47], v[104:107], v[168:171], v[44:47]
	v_mfma_f32_16x16x32_bf16 v[40:43], v[120:123], v[168:171], v[40:43]
	v_mfma_f32_16x16x32_bf16 v[28:31], v[104:107], v[176:179], v[28:31]
	v_mfma_f32_16x16x32_bf16 v[24:27], v[120:123], v[176:179], v[24:27]
	v_mfma_f32_16x16x32_bf16 v[12:15], v[104:107], v[184:187], v[12:15]
	v_mfma_f32_16x16x32_bf16 v[8:11], v[120:123], v[184:187], v[8:11]
	v_mfma_f32_16x16x32_bf16 v[60:63], v[108:111], v[164:167], v[60:63]
	v_mfma_f32_16x16x32_bf16 v[56:59], v[124:127], v[164:167], v[56:59]
	v_mfma_f32_16x16x32_bf16 v[44:47], v[108:111], v[172:175], v[44:47]
	v_mfma_f32_16x16x32_bf16 v[40:43], v[124:127], v[172:175], v[40:43]
	v_mfma_f32_16x16x32_bf16 v[28:31], v[108:111], v[180:183], v[28:31]
	v_mfma_f32_16x16x32_bf16 v[24:27], v[124:127], v[180:183], v[24:27]
	v_mfma_f32_16x16x32_bf16 v[12:15], v[108:111], v[188:191], v[12:15]
	v_mfma_f32_16x16x32_bf16 v[8:11], v[124:127], v[188:191], v[8:11]
	s_setprio 0
	s_setprio 1
	v_mfma_f32_16x16x32_bf16 v[52:55], v[136:139], v[160:163], v[52:55]
	v_mfma_f32_16x16x32_bf16 v[48:51], v[152:155], v[160:163], v[48:51]
	v_mfma_f32_16x16x32_bf16 v[36:39], v[136:139], v[168:171], v[36:39]
	v_mfma_f32_16x16x32_bf16 v[32:35], v[152:155], v[168:171], v[32:35]
	v_mfma_f32_16x16x32_bf16 v[20:23], v[136:139], v[176:179], v[20:23]
	v_mfma_f32_16x16x32_bf16 v[16:19], v[152:155], v[176:179], v[16:19]
	v_mfma_f32_16x16x32_bf16 v[4:7], v[136:139], v[184:187], v[4:7]
	v_mfma_f32_16x16x32_bf16 v[0:3], v[152:155], v[184:187], v[0:3]
	v_mfma_f32_16x16x32_bf16 v[52:55], v[140:143], v[164:167], v[52:55]
	v_mfma_f32_16x16x32_bf16 v[48:51], v[156:159], v[164:167], v[48:51]
	v_mfma_f32_16x16x32_bf16 v[36:39], v[140:143], v[172:175], v[36:39]
	v_mfma_f32_16x16x32_bf16 v[32:35], v[156:159], v[172:175], v[32:35]
	v_mfma_f32_16x16x32_bf16 v[20:23], v[140:143], v[180:183], v[20:23]
	v_mfma_f32_16x16x32_bf16 v[16:19], v[156:159], v[180:183], v[16:19]
	v_mfma_f32_16x16x32_bf16 v[4:7], v[140:143], v[188:191], v[4:7]
	v_mfma_f32_16x16x32_bf16 v[0:3], v[156:159], v[188:191], v[0:3]
	s_setprio 0
	s_barrier
	s_add_i32 s51, 0, 0x18000
	s_add_i32 s70, 0, 0x1c000
	v_add_u32_e32 v124, s51, v221
	v_add_u32_e32 v156, s70, v221
	ds_read_b128 v[104:107], v124
	ds_read_b128 v[108:111], v124 offset:1024
	ds_read_b128 v[120:123], v124 offset:2048
	ds_read_b128 v[124:127], v124 offset:3072
	ds_read_b128 v[136:139], v156
	ds_read_b128 v[140:143], v156 offset:1024
	ds_read_b128 v[152:155], v156 offset:2048
	ds_read_b128 v[156:159], v156 offset:3072
	s_add_u32 s42, s42, 0x80000
	s_addc_u32 s43, s43, 0
	s_mov_b32 m0, s55
	v_lshl_add_u64 v[216:217], s[42:43], 0, v[194:195]
	ds_read_b128 v[160:163], v226 offset:32768
	ds_read_b128 v[164:167], v226 offset:33792
	ds_read_b128 v[168:171], v226 offset:34816
	ds_read_b128 v[172:175], v226 offset:35840
	ds_read_b128 v[176:179], v226 offset:36864
	ds_read_b128 v[180:183], v226 offset:37888
	ds_read_b128 v[184:187], v226 offset:38912
	ds_read_b128 v[188:191], v226 offset:39936
	global_load_lds_dwordx4 v[216:217], off
	v_lshl_add_u64 v[216:217], s[42:43], 0, v[198:199]
	s_mov_b32 m0, s56
	s_nop 0
	global_load_lds_dwordx4 v[216:217], off
	s_waitcnt vmcnt(8)
	s_waitcnt lgkmcnt(0)
	s_barrier
	s_setprio 1
	v_mfma_f32_16x16x32_bf16 v[148:151], v[104:107], v[160:163], v[148:151]
	v_mfma_f32_16x16x32_bf16 v[144:147], v[120:123], v[160:163], v[144:147]
	v_mfma_f32_16x16x32_bf16 v[116:119], v[104:107], v[168:171], v[116:119]
	v_mfma_f32_16x16x32_bf16 v[112:115], v[120:123], v[168:171], v[112:115]
	v_mfma_f32_16x16x32_bf16 v[92:95], v[104:107], v[176:179], v[92:95]
	v_mfma_f32_16x16x32_bf16 v[88:91], v[120:123], v[176:179], v[88:91]
	v_mfma_f32_16x16x32_bf16 v[76:79], v[104:107], v[184:187], v[76:79]
	v_mfma_f32_16x16x32_bf16 v[72:75], v[120:123], v[184:187], v[72:75]
	v_mfma_f32_16x16x32_bf16 v[148:151], v[108:111], v[164:167], v[148:151]
	v_mfma_f32_16x16x32_bf16 v[144:147], v[124:127], v[164:167], v[144:147]
	v_mfma_f32_16x16x32_bf16 v[116:119], v[108:111], v[172:175], v[116:119]
	v_mfma_f32_16x16x32_bf16 v[112:115], v[124:127], v[172:175], v[112:115]
	v_mfma_f32_16x16x32_bf16 v[92:95], v[108:111], v[180:183], v[92:95]
	v_mfma_f32_16x16x32_bf16 v[88:91], v[124:127], v[180:183], v[88:91]
	v_mfma_f32_16x16x32_bf16 v[76:79], v[108:111], v[188:191], v[76:79]
	v_mfma_f32_16x16x32_bf16 v[72:75], v[124:127], v[188:191], v[72:75]
	s_setprio 0
	s_setprio 1
	v_mfma_f32_16x16x32_bf16 v[132:135], v[136:139], v[160:163], v[132:135]
	v_mfma_f32_16x16x32_bf16 v[128:131], v[152:155], v[160:163], v[128:131]
	v_mfma_f32_16x16x32_bf16 v[100:103], v[136:139], v[168:171], v[100:103]
	v_mfma_f32_16x16x32_bf16 v[96:99], v[152:155], v[168:171], v[96:99]
	v_mfma_f32_16x16x32_bf16 v[84:87], v[136:139], v[176:179], v[84:87]
	v_mfma_f32_16x16x32_bf16 v[80:83], v[152:155], v[176:179], v[80:83]
	v_mfma_f32_16x16x32_bf16 v[68:71], v[136:139], v[184:187], v[68:71]
	v_mfma_f32_16x16x32_bf16 v[64:67], v[152:155], v[184:187], v[64:67]
	v_mfma_f32_16x16x32_bf16 v[132:135], v[140:143], v[164:167], v[132:135]
	v_mfma_f32_16x16x32_bf16 v[128:131], v[156:159], v[164:167], v[128:131]
	v_mfma_f32_16x16x32_bf16 v[100:103], v[140:143], v[172:175], v[100:103]
	v_mfma_f32_16x16x32_bf16 v[96:99], v[156:159], v[172:175], v[96:99]
	v_mfma_f32_16x16x32_bf16 v[84:87], v[140:143], v[180:183], v[84:87]
	v_mfma_f32_16x16x32_bf16 v[80:83], v[156:159], v[180:183], v[80:83]
	v_mfma_f32_16x16x32_bf16 v[68:71], v[140:143], v[188:191], v[68:71]
	v_mfma_f32_16x16x32_bf16 v[64:67], v[156:159], v[188:191], v[64:67]
	s_setprio 0
	s_barrier
; #define PG8_STAGE(bufoff, gbase, voff) do { _Pragma("unroll") for (int _i = 0; _i < 2; ++_i) \
;         __builtin_amdgcn_global_load_lds((const unsigned*)((const char*)(gbase) + (voff)[_i]), (LAS unsigned*)(lds + (bufoff) + ldsw + _i * 8192), 16, 0, 0); } while (0)
; #define PG8_LDA(dst, b, h) do { _Pragma("unroll") for (int m = 0; m < 4; ++m) _Pragma("unroll") for (int k = 0; k < 2; ++k) dst[m][k] = *(const LAS bf16x8*)(lds + PG8_SA(b, h) + aoff + m * 2048 + k * 1024); } while (0)
; #define PG8_MMA(ai, bj, At, Bt) do { __builtin_amdgcn_s_setprio(1); _Pragma("unroll") for (int m = 0; m < 4; ++m) _Pragma("unroll") for (int n = 0; n < 2; ++n) _Pragma("unroll") for (int k = 0; k < 2; ++k) \
;         acc[ai][bj][m][n] = __builtin_amdgcn_mfma_f32_16x16x32_bf16(Bt[n][k], At[m][k], acc[ai][bj][m][n], 0, 0, 0); __builtin_amdgcn_s_setprio(0); } while (0)
; #define PG8_WAIT_V(n) asm volatile("s_waitcnt vmcnt(" #n ")" ::: "memory")
; #define PG8_WAIT_L(n) asm volatile("s_waitcnt lgkmcnt(" #n ")" ::: "memory")
; #define PG8_BAR __builtin_amdgcn_s_barrier()
; #define PG8_SCHED __builtin_amdgcn_sched_barrier(0)
; template <class Epi, class Sched = StaticOrder, class EpiSub = NoSub, bool FAST = false>
; __device__ __forceinline__ void gemm_phase(LAS unsigned char* lds, const Gemm g, const Sched& S, const Epi& E, const EpiSub& ES = EpiSub()) {
;     ...
;             PG8_LDA(At, 1, 1); PG8_STAGE(PG8_SB(1, 0), b3, voffB); PG8_STAGE(PG8_SB(1, 1), b3 + hstepB, voffB); PG8_STAGE(PG8_SA(1, 0), a3, voffA);
;             PG8_WAIT_V(8); PG8_WAIT_L(0); PG8_BAR; PG8_MMA(1, 0, At, B0); PG8_MMA(1, 1, At, B1); PG8_BAR; PG8_SCHED;
;     ...
;         if constexpr (FAST && PG8_ALIGN) { if (wr == 0) PG8_BAR; }
	s_add_i32 s42, s51, s52
	v_lshl_add_u64 v[208:209], v[208:209], 0, s[12:13]
	s_mov_b32 m0, s42
	ds_read_b128 v[160:163], v226 offset:49152
	ds_read_b128 v[164:167], v226 offset:50176
	ds_read_b128 v[168:171], v226 offset:51200
	ds_read_b128 v[172:175], v226 offset:52224
	ds_read_b128 v[176:179], v226 offset:53248
	ds_read_b128 v[180:183], v226 offset:54272
	ds_read_b128 v[184:187], v226 offset:55296
	ds_read_b128 v[188:191], v226 offset:56320
	global_load_lds_dwordx4 v[208:209], off
	s_add_i32 m0, s42, 0x2000
	s_add_u32 s40, s40, 0x80080
	v_lshl_add_u64 v[208:209], v[210:211], 0, s[12:13]
	s_addc_u32 s41, s41, 0
	s_add_i32 s42, s70, s52
	global_load_lds_dwordx4 v[208:209], off
	v_lshl_add_u64 v[208:209], s[40:41], 0, v[196:197]
	s_mov_b32 m0, s42
	s_nop 0
	global_load_lds_dwordx4 v[208:209], off
	v_lshl_add_u64 v[208:209], s[40:41], 0, v[200:201]
	s_add_i32 m0, s42, 0x2000
	s_nop 0
	global_load_lds_dwordx4 v[208:209], off
	v_lshl_add_u64 v[208:209], v[212:213], 0, s[12:13]
	s_mov_b32 m0, s69
	s_nop 0
	global_load_lds_dwordx4 v[208:209], off
	v_lshl_add_u64 v[208:209], v[214:215], 0, s[12:13]
	s_mov_b32 m0, s74
	s_nop 0
	global_load_lds_dwordx4 v[208:209], off
	s_waitcnt vmcnt(8)
	s_waitcnt lgkmcnt(0)
	s_barrier
	s_setprio 1
	v_mfma_f32_16x16x32_bf16 v[60:63], v[104:107], v[160:163], v[60:63]
	v_mfma_f32_16x16x32_bf16 v[56:59], v[120:123], v[160:163], v[56:59]
	v_mfma_f32_16x16x32_bf16 v[44:47], v[104:107], v[168:171], v[44:47]
	v_mfma_f32_16x16x32_bf16 v[40:43], v[120:123], v[168:171], v[40:43]
	v_mfma_f32_16x16x32_bf16 v[28:31], v[104:107], v[176:179], v[28:31]
	v_mfma_f32_16x16x32_bf16 v[24:27], v[120:123], v[176:179], v[24:27]
	v_mfma_f32_16x16x32_bf16 v[12:15], v[104:107], v[184:187], v[12:15]
	v_mfma_f32_16x16x32_bf16 v[8:11], v[120:123], v[184:187], v[8:11]
	v_mfma_f32_16x16x32_bf16 v[60:63], v[108:111], v[164:167], v[60:63]
	v_mfma_f32_16x16x32_bf16 v[56:59], v[124:127], v[164:167], v[56:59]
	v_mfma_f32_16x16x32_bf16 v[44:47], v[108:111], v[172:175], v[44:47]
	v_mfma_f32_16x16x32_bf16 v[40:43], v[124:127], v[172:175], v[40:43]
	v_mfma_f32_16x16x32_bf16 v[28:31], v[108:111], v[180:183], v[28:31]
	v_mfma_f32_16x16x32_bf16 v[24:27], v[124:127], v[180:183], v[24:27]
	v_mfma_f32_16x16x32_bf16 v[12:15], v[108:111], v[188:191], v[12:15]
	v_mfma_f32_16x16x32_bf16 v[8:11], v[124:127], v[188:191], v[8:11]
	s_setprio 0
	s_setprio 1
	v_mfma_f32_16x16x32_bf16 v[52:55], v[136:139], v[160:163], v[52:55]
	v_mfma_f32_16x16x32_bf16 v[48:51], v[152:155], v[160:163], v[48:51]
	v_mfma_f32_16x16x32_bf16 v[36:39], v[136:139], v[168:171], v[36:39]
	v_mfma_f32_16x16x32_bf16 v[32:35], v[152:155], v[168:171], v[32:35]
	v_mfma_f32_16x16x32_bf16 v[20:23], v[136:139], v[176:179], v[20:23]
	v_mfma_f32_16x16x32_bf16 v[16:19], v[152:155], v[176:179], v[16:19]
	v_mfma_f32_16x16x32_bf16 v[4:7], v[136:139], v[184:187], v[4:7]
	v_mfma_f32_16x16x32_bf16 v[0:3], v[152:155], v[184:187], v[0:3]
	v_mfma_f32_16x16x32_bf16 v[52:55], v[140:143], v[164:167], v[52:55]
	v_mfma_f32_16x16x32_bf16 v[48:51], v[156:159], v[164:167], v[48:51]
	v_mfma_f32_16x16x32_bf16 v[36:39], v[140:143], v[172:175], v[36:39]
	v_mfma_f32_16x16x32_bf16 v[32:35], v[156:159], v[172:175], v[32:35]
	v_mfma_f32_16x16x32_bf16 v[20:23], v[140:143], v[180:183], v[20:23]
	v_mfma_f32_16x16x32_bf16 v[16:19], v[156:159], v[180:183], v[16:19]
	v_mfma_f32_16x16x32_bf16 v[4:7], v[140:143], v[188:191], v[4:7]
	v_mfma_f32_16x16x32_bf16 v[0:3], v[156:159], v[188:191], v[0:3]
	s_setprio 0
	s_barrier
	s_add_u32 s38, s38, 0x100
	s_addc_u32 s39, s39, 0
	s_add_u32 s48, s48, 0x100
	s_addc_u32 s49, s49, 0
	s_cmp_ge_u32 s50, s31
	s_mov_b32 s42, s50
	s_cbranch_scc0 .LBB0_632
	s_and_b64 vcc, exec, s[14:15]
	s_cbranch_vccz .LBB0_635
	s_barrier

; #define PG8_STAGE(bufoff, gbase, voff) do { _Pragma("unroll") for (int _i = 0; _i < 2; ++_i) \
;         __builtin_amdgcn_global_load_lds((const unsigned*)((const char*)(gbase) + (voff)[_i]), (LAS unsigned*)(lds + (bufoff) + ldsw + _i * 8192), 16, 0, 0); } while (0)
; #define PG8_LDA(dst, b, h) do { _Pragma("unroll") for (int m = 0; m < 4; ++m) _Pragma("unroll") for (int k = 0; k < 2; ++k) dst[m][k] = *(const LAS bf16x8*)(lds + PG8_SA(b, h) + aoff + m * 2048 + k * 1024); } while (0)
; #define PG8_LDB(dst, b, h) do { _Pragma("unroll") for (int n = 0; n < 2; ++n) _Pragma("unroll") for (int k = 0; k < 2; ++k) dst[n][k] = *(const LAS bf16x8*)(lds + PG8_SB(b, h) + boff + n * 2048 + k * 1024); } while (0)
; #define PG8_WAIT_V(n) asm volatile("s_waitcnt vmcnt(" #n ")" ::: "memory")
; #define PG8_BAR __builtin_amdgcn_s_barrier()
; template <class Epi, class Sched = StaticOrder, class EpiSub = NoSub, bool FAST = false>
; __device__ __forceinline__ void gemm_phase(LAS unsigned char* lds, const Gemm g, const Sched& S, const Epi& E, const EpiSub& ES = EpiSub()) {
;     ...
;         const bool has_next = S.next(ui + 1, nxt);
;         const size_t nko = (has_next && nxt.kb >= 0) ? nxt.kb * ksubB : 0;
;         const char* nA = has_next ? (const char*)g.A + (size_t)nxt.pm * tstepA + (size_t)nxt.pn * g.acs + nko : cA; const char* nB = has_next ? (const char*)g.Bt + (size_t)nxt.pn * tstepB + nko : cB;
;         const int nt = cur.kb < 0 ? ntMain : ntSub;
;         for (int t = 0; t < nt; t += 2) {
;             const bool last = (t == nt - 2);
;             const char* a1 = cA + (size_t)(t + 1) * kstep;
;             const char* a2 = last ? nA : cA + (size_t)(t + 2) * kstep; const char* b2 = last ? nB : cB + (size_t)(t + 2) * kstep;
;             const char* a3 = a2 + kstep; const char* b3 = b2 + kstep;
;             if constexpr (FAST && PG8_SP2) {
;             PG8_LDB(B0, 0, 0); PG8_LDB(B1, 0, 1); PG8_SCHED; PG8_LDA(At, 0, 0); PG8_STAGE(PG8_SA(1, 1), a1 + hstepA, voffA);
;             PG8_WAIT_V(8); PG8_WAIT_L(0); PG8_BAR; PG8_MMA(0, 0, At, B0); PG8_MMA(0, 1, At, B1); PG8_BAR; PG8_SCHED;
;             PG8_LDA(At, 0, 1); PG8_STAGE(PG8_SB(0, 0), b2, voffB); PG8_STAGE(PG8_SB(0, 1), b2 + hstepB, voffB); PG8_STAGE(PG8_SA(0, 0), a2, voffA);
;             PG8_WAIT_V(8); PG8_WAIT_L(0); PG8_BAR; PG8_MMA(1, 0, At, B0); PG8_MMA(1, 1, At, B1); PG8_BAR; PG8_SCHED;
.LBB0_769:
	ds_read_b128 v[96:99], v215
	ds_read_b128 v[100:103], v215 offset:1024
	ds_read_b128 v[112:115], v215 offset:2048
	ds_read_b128 v[116:119], v215 offset:3072
	ds_read_b128 v[144:147], v216
	ds_read_b128 v[148:151], v216 offset:1024
	ds_read_b128 v[152:155], v216 offset:2048
	ds_read_b128 v[156:159], v216 offset:3072
	s_add_i32 s72, s42, 2
	s_add_u32 s40, s38, 0xfff80080
	s_addc_u32 s41, s39, -1
	s_cmp_eq_u32 s33, s42
	s_cselect_b32 s42, s5, s40
	s_cselect_b32 s43, s1, s41
	s_cselect_b32 s41, s19, s71
	s_cselect_b32 s40, s21, s70
	v_lshl_add_u64 v[208:209], s[38:39], 0, v[194:195]
	s_add_i32 m0, s48, 0xc000
	ds_read_b128 v[160:163], v217
	ds_read_b128 v[164:167], v217 offset:1024
	ds_read_b128 v[168:171], v217 offset:2048
	ds_read_b128 v[172:175], v217 offset:3072
	ds_read_b128 v[176:179], v217 offset:4096
	ds_read_b128 v[180:183], v217 offset:5120
	ds_read_b128 v[200:203], v217 offset:6144
	ds_read_b128 v[204:207], v217 offset:7168
	global_load_lds_dwordx4 v[208:209], off
	v_lshl_add_u64 v[208:209], s[38:39], 0, v[196:197]
	s_add_i32 m0, s48, 0xe000
	s_nop 0
	global_load_lds_dwordx4 v[208:209], off
	s_waitcnt vmcnt(8)
	s_waitcnt lgkmcnt(0)
	s_barrier
	s_setprio 1
	v_mfma_f32_16x16x32_bf16 v[140:143], v[96:99], v[160:163], v[140:143]
	v_mfma_f32_16x16x32_bf16 v[136:139], v[112:115], v[160:163], v[136:139]
	v_mfma_f32_16x16x32_bf16 v[124:127], v[96:99], v[168:171], v[124:127]
	v_mfma_f32_16x16x32_bf16 v[120:123], v[112:115], v[168:171], v[120:123]
	v_mfma_f32_16x16x32_bf16 v[92:95], v[96:99], v[176:179], v[92:95]
	v_mfma_f32_16x16x32_bf16 v[88:91], v[112:115], v[176:179], v[88:91]
	v_mfma_f32_16x16x32_bf16 v[76:79], v[96:99], v[200:203], v[76:79]
	v_mfma_f32_16x16x32_bf16 v[72:75], v[112:115], v[200:203], v[72:75]
	v_mfma_f32_16x16x32_bf16 v[140:143], v[100:103], v[164:167], v[140:143]
	v_mfma_f32_16x16x32_bf16 v[136:139], v[116:119], v[164:167], v[136:139]
	v_mfma_f32_16x16x32_bf16 v[124:127], v[100:103], v[172:175], v[124:127]
	v_mfma_f32_16x16x32_bf16 v[120:123], v[116:119], v[172:175], v[120:123]
	v_mfma_f32_16x16x32_bf16 v[92:95], v[100:103], v[180:183], v[92:95]
	v_mfma_f32_16x16x32_bf16 v[88:91], v[116:119], v[180:183], v[88:91]
	v_mfma_f32_16x16x32_bf16 v[76:79], v[100:103], v[204:207], v[76:79]
	v_mfma_f32_16x16x32_bf16 v[72:75], v[116:119], v[204:207], v[72:75]
	s_setprio 0
	s_setprio 1
	v_mfma_f32_16x16x32_bf16 v[132:135], v[144:147], v[160:163], v[132:135]
	v_mfma_f32_16x16x32_bf16 v[128:131], v[152:155], v[160:163], v[128:131]
	v_mfma_f32_16x16x32_bf16 v[108:111], v[144:147], v[168:171], v[108:111]
	v_mfma_f32_16x16x32_bf16 v[104:107], v[152:155], v[168:171], v[104:107]
	v_mfma_f32_16x16x32_bf16 v[84:87], v[144:147], v[176:179], v[84:87]
	v_mfma_f32_16x16x32_bf16 v[80:83], v[152:155], v[176:179], v[80:83]
	v_mfma_f32_16x16x32_bf16 v[68:71], v[144:147], v[200:203], v[68:71]
	v_mfma_f32_16x16x32_bf16 v[64:67], v[152:155], v[200:203], v[64:67]
	v_mfma_f32_16x16x32_bf16 v[132:135], v[148:151], v[164:167], v[132:135]
	v_mfma_f32_16x16x32_bf16 v[128:131], v[156:159], v[164:167], v[128:131]
	v_mfma_f32_16x16x32_bf16 v[108:111], v[148:151], v[172:175], v[108:111]
	v_mfma_f32_16x16x32_bf16 v[104:107], v[156:159], v[172:175], v[104:107]
	v_mfma_f32_16x16x32_bf16 v[84:87], v[148:151], v[180:183], v[84:87]
	v_mfma_f32_16x16x32_bf16 v[80:83], v[156:159], v[180:183], v[80:83]
	v_mfma_f32_16x16x32_bf16 v[68:71], v[148:151], v[204:207], v[68:71]
	v_mfma_f32_16x16x32_bf16 v[64:67], v[156:159], v[204:207], v[64:67]
	s_setprio 0
	s_barrier
	s_add_i32 s73, s58, s17
	v_lshl_add_u64 v[208:209], s[40:41], 0, v[186:187]
	s_mov_b32 m0, s73
	ds_read_b128 v[160:163], v217 offset:16384
	ds_read_b128 v[164:167], v217 offset:17408
	ds_read_b128 v[168:171], v217 offset:18432
	ds_read_b128 v[172:175], v217 offset:19456
	ds_read_b128 v[176:179], v217 offset:20480
	ds_read_b128 v[180:183], v217 offset:21504
	ds_read_b128 v[200:203], v217 offset:22528
	ds_read_b128 v[204:207], v217 offset:23552
	global_load_lds_dwordx4 v[208:209], off
	s_add_i32 m0, s73, 0x2000
	s_add_u32 s76, s40, 0x80000
	v_lshl_add_u64 v[210:211], s[40:41], 0, v[190:191]
	s_addc_u32 s77, s41, 0
	s_add_i32 s73, s59, s17
	global_load_lds_dwordx4 v[210:211], off
	v_lshl_add_u64 v[218:219], s[76:77], 0, v[186:187]
	s_mov_b32 m0, s73
	v_lshl_add_u64 v[220:221], s[42:43], 0, v[188:189]
	global_load_lds_dwordx4 v[218:219], off
	v_lshl_add_u64 v[218:219], s[76:77], 0, v[190:191]
	s_add_i32 m0, s73, 0x2000
	s_nop 0
	global_load_lds_dwordx4 v[218:219], off
	v_lshl_add_u64 v[218:219], s[42:43], 0, v[184:185]
	s_mov_b32 m0, s48
	s_nop 0
	global_load_lds_dwordx4 v[218:219], off
	s_mov_b32 m0, s49
	s_nop 0
	global_load_lds_dwordx4 v[220:221], off
	s_waitcnt vmcnt(8)
	s_waitcnt lgkmcnt(0)
	s_barrier
; #define PG8_STAGE(bufoff, gbase, voff) do { _Pragma("unroll") for (int _i = 0; _i < 2; ++_i) \
;         __builtin_amdgcn_global_load_lds((const unsigned*)((const char*)(gbase) + (voff)[_i]), (LAS unsigned*)(lds + (bufoff) + ldsw + _i * 8192), 16, 0, 0); } while (0)
; #define PG8_LDA(dst, b, h) do { _Pragma("unroll") for (int m = 0; m < 4; ++m) _Pragma("unroll") for (int k = 0; k < 2; ++k) dst[m][k] = *(const LAS bf16x8*)(lds + PG8_SA(b, h) + aoff + m * 2048 + k * 1024); } while (0)
; #define PG8_LDB(dst, b, h) do { _Pragma("unroll") for (int n = 0; n < 2; ++n) _Pragma("unroll") for (int k = 0; k < 2; ++k) dst[n][k] = *(const LAS bf16x8*)(lds + PG8_SB(b, h) + boff + n * 2048 + k * 1024); } while (0)
; #define PG8_MMA(ai, bj, At, Bt) do { __builtin_amdgcn_s_setprio(1); _Pragma("unroll") for (int m = 0; m < 4; ++m) _Pragma("unroll") for (int n = 0; n < 2; ++n) _Pragma("unroll") for (int k = 0; k < 2; ++k) \
;         acc[ai][bj][m][n] = __builtin_amdgcn_mfma_f32_16x16x32_bf16(Bt[n][k], At[m][k], acc[ai][bj][m][n], 0, 0, 0); __builtin_amdgcn_s_setprio(0); } while (0)
; #define PG8_WAIT_V(n) asm volatile("s_waitcnt vmcnt(" #n ")" ::: "memory")
; #define PG8_WAIT_L(n) asm volatile("s_waitcnt lgkmcnt(" #n ")" ::: "memory")
; #define PG8_BAR __builtin_amdgcn_s_barrier()
; #define PG8_SCHED __builtin_amdgcn_sched_barrier(0)
; template <class Epi, class Sched = StaticOrder, class EpiSub = NoSub, bool FAST = false>
; __device__ __forceinline__ void gemm_phase(LAS unsigned char* lds, const Gemm g, const Sched& S, const Epi& E, const EpiSub& ES = EpiSub()) {
;     ...
;             PG8_WAIT_V(8); PG8_WAIT_L(0); PG8_BAR; PG8_MMA(1, 0, At, B0); PG8_MMA(1, 1, At, B1); PG8_BAR; PG8_SCHED;
;             PG8_LDB(B0, 1, 0); PG8_LDB(B1, 1, 1); PG8_SCHED; PG8_LDA(At, 1, 0); PG8_STAGE(PG8_SA(0, 1), a2 + hstepA, voffA);
;             PG8_WAIT_V(8); PG8_WAIT_L(0); PG8_BAR; PG8_MMA(0, 0, At, B0); PG8_MMA(0, 1, At, B1); PG8_BAR; PG8_SCHED;
	s_setprio 1
	v_mfma_f32_16x16x32_bf16 v[60:63], v[96:99], v[160:163], v[60:63]
	v_mfma_f32_16x16x32_bf16 v[56:59], v[112:115], v[160:163], v[56:59]
	v_mfma_f32_16x16x32_bf16 v[44:47], v[96:99], v[168:171], v[44:47]
	v_mfma_f32_16x16x32_bf16 v[40:43], v[112:115], v[168:171], v[40:43]
	v_mfma_f32_16x16x32_bf16 v[28:31], v[96:99], v[176:179], v[28:31]
	v_mfma_f32_16x16x32_bf16 v[24:27], v[112:115], v[176:179], v[24:27]
	v_mfma_f32_16x16x32_bf16 v[12:15], v[96:99], v[200:203], v[12:15]
	v_mfma_f32_16x16x32_bf16 v[8:11], v[112:115], v[200:203], v[8:11]
	v_mfma_f32_16x16x32_bf16 v[60:63], v[100:103], v[164:167], v[60:63]
	v_mfma_f32_16x16x32_bf16 v[56:59], v[116:119], v[164:167], v[56:59]
	v_mfma_f32_16x16x32_bf16 v[44:47], v[100:103], v[172:175], v[44:47]
	v_mfma_f32_16x16x32_bf16 v[40:43], v[116:119], v[172:175], v[40:43]
	v_mfma_f32_16x16x32_bf16 v[28:31], v[100:103], v[180:183], v[28:31]
	v_mfma_f32_16x16x32_bf16 v[24:27], v[116:119], v[180:183], v[24:27]
	v_mfma_f32_16x16x32_bf16 v[12:15], v[100:103], v[204:207], v[12:15]
	v_mfma_f32_16x16x32_bf16 v[8:11], v[116:119], v[204:207], v[8:11]
	s_setprio 0
	s_setprio 1
	v_mfma_f32_16x16x32_bf16 v[52:55], v[144:147], v[160:163], v[52:55]
	v_mfma_f32_16x16x32_bf16 v[48:51], v[152:155], v[160:163], v[48:51]
	v_mfma_f32_16x16x32_bf16 v[36:39], v[144:147], v[168:171], v[36:39]
	v_mfma_f32_16x16x32_bf16 v[32:35], v[152:155], v[168:171], v[32:35]
	v_mfma_f32_16x16x32_bf16 v[20:23], v[144:147], v[176:179], v[20:23]
	v_mfma_f32_16x16x32_bf16 v[16:19], v[152:155], v[176:179], v[16:19]
	v_mfma_f32_16x16x32_bf16 v[4:7], v[144:147], v[200:203], v[4:7]
	v_mfma_f32_16x16x32_bf16 v[0:3], v[152:155], v[200:203], v[0:3]
	v_mfma_f32_16x16x32_bf16 v[52:55], v[148:151], v[164:167], v[52:55]
	v_mfma_f32_16x16x32_bf16 v[48:51], v[156:159], v[164:167], v[48:51]
	v_mfma_f32_16x16x32_bf16 v[36:39], v[148:151], v[172:175], v[36:39]
	v_mfma_f32_16x16x32_bf16 v[32:35], v[156:159], v[172:175], v[32:35]
	v_mfma_f32_16x16x32_bf16 v[20:23], v[148:151], v[180:183], v[20:23]
	v_mfma_f32_16x16x32_bf16 v[16:19], v[156:159], v[180:183], v[16:19]
	v_mfma_f32_16x16x32_bf16 v[4:7], v[148:151], v[204:207], v[4:7]
	v_mfma_f32_16x16x32_bf16 v[0:3], v[156:159], v[204:207], v[0:3]
	s_setprio 0
	s_barrier
	s_add_i32 s73, 0, 0x18000
	s_add_i32 s76, 0, 0x1c000
	v_add_u32_e32 v116, s73, v212
	v_add_u32_e32 v156, s76, v212
	ds_read_b128 v[96:99], v116
	ds_read_b128 v[100:103], v116 offset:1024
	ds_read_b128 v[112:115], v116 offset:2048
	ds_read_b128 v[116:119], v116 offset:3072
	ds_read_b128 v[144:147], v156
	ds_read_b128 v[148:151], v156 offset:1024
	ds_read_b128 v[152:155], v156 offset:2048
	ds_read_b128 v[156:159], v156 offset:3072
	s_add_u32 s42, s42, 0x80000
	s_addc_u32 s43, s43, 0
	s_mov_b32 m0, s50
	v_lshl_add_u64 v[222:223], s[42:43], 0, v[184:185]
	ds_read_b128 v[160:163], v217 offset:32768
	ds_read_b128 v[164:167], v217 offset:33792
	ds_read_b128 v[168:171], v217 offset:34816
	ds_read_b128 v[172:175], v217 offset:35840
	ds_read_b128 v[176:179], v217 offset:36864
	ds_read_b128 v[180:183], v217 offset:37888
	ds_read_b128 v[200:203], v217 offset:38912
	ds_read_b128 v[204:207], v217 offset:39936
	global_load_lds_dwordx4 v[222:223], off
	v_lshl_add_u64 v[222:223], s[42:43], 0, v[188:189]
	s_mov_b32 m0, s51
	s_nop 0
	global_load_lds_dwordx4 v[222:223], off
	s_waitcnt vmcnt(8)
	s_waitcnt lgkmcnt(0)
	s_barrier
	s_setprio 1
	v_mfma_f32_16x16x32_bf16 v[140:143], v[96:99], v[160:163], v[140:143]
	v_mfma_f32_16x16x32_bf16 v[136:139], v[112:115], v[160:163], v[136:139]
	v_mfma_f32_16x16x32_bf16 v[124:127], v[96:99], v[168:171], v[124:127]
	v_mfma_f32_16x16x32_bf16 v[120:123], v[112:115], v[168:171], v[120:123]
	v_mfma_f32_16x16x32_bf16 v[92:95], v[96:99], v[176:179], v[92:95]
	v_mfma_f32_16x16x32_bf16 v[88:91], v[112:115], v[176:179], v[88:91]
	v_mfma_f32_16x16x32_bf16 v[76:79], v[96:99], v[200:203], v[76:79]
	v_mfma_f32_16x16x32_bf16 v[72:75], v[112:115], v[200:203], v[72:75]
	v_mfma_f32_16x16x32_bf16 v[140:143], v[100:103], v[164:167], v[140:143]
	v_mfma_f32_16x16x32_bf16 v[136:139], v[116:119], v[164:167], v[136:139]
	v_mfma_f32_16x16x32_bf16 v[124:127], v[100:103], v[172:175], v[124:127]
	v_mfma_f32_16x16x32_bf16 v[120:123], v[116:119], v[172:175], v[120:123]
	v_mfma_f32_16x16x32_bf16 v[92:95], v[100:103], v[180:183], v[92:95]
	v_mfma_f32_16x16x32_bf16 v[88:91], v[116:119], v[180:183], v[88:91]
	v_mfma_f32_16x16x32_bf16 v[76:79], v[100:103], v[204:207], v[76:79]
	v_mfma_f32_16x16x32_bf16 v[72:75], v[116:119], v[204:207], v[72:75]
	s_setprio 0
	s_setprio 1
	v_mfma_f32_16x16x32_bf16 v[132:135], v[144:147], v[160:163], v[132:135]
	v_mfma_f32_16x16x32_bf16 v[128:131], v[152:155], v[160:163], v[128:131]
	v_mfma_f32_16x16x32_bf16 v[108:111], v[144:147], v[168:171], v[108:111]
	v_mfma_f32_16x16x32_bf16 v[104:107], v[152:155], v[168:171], v[104:107]
	v_mfma_f32_16x16x32_bf16 v[84:87], v[144:147], v[176:179], v[84:87]
	v_mfma_f32_16x16x32_bf16 v[80:83], v[152:155], v[176:179], v[80:83]
	v_mfma_f32_16x16x32_bf16 v[68:71], v[144:147], v[200:203], v[68:71]
	v_mfma_f32_16x16x32_bf16 v[64:67], v[152:155], v[200:203], v[64:67]
	v_mfma_f32_16x16x32_bf16 v[132:135], v[148:151], v[164:167], v[132:135]
	v_mfma_f32_16x16x32_bf16 v[128:131], v[156:159], v[164:167], v[128:131]
	v_mfma_f32_16x16x32_bf16 v[108:111], v[148:151], v[172:175], v[108:111]
	v_mfma_f32_16x16x32_bf16 v[104:107], v[156:159], v[172:175], v[104:107]
	v_mfma_f32_16x16x32_bf16 v[84:87], v[148:151], v[180:183], v[84:87]
	v_mfma_f32_16x16x32_bf16 v[80:83], v[156:159], v[180:183], v[80:83]
	v_mfma_f32_16x16x32_bf16 v[68:71], v[148:151], v[204:207], v[68:71]
	v_mfma_f32_16x16x32_bf16 v[64:67], v[156:159], v[204:207], v[64:67]
	s_setprio 0
	s_barrier
; #define PG8_STAGE(bufoff, gbase, voff) do { _Pragma("unroll") for (int _i = 0; _i < 2; ++_i) \
;         __builtin_amdgcn_global_load_lds((const unsigned*)((const char*)(gbase) + (voff)[_i]), (LAS unsigned*)(lds + (bufoff) + ldsw + _i * 8192), 16, 0, 0); } while (0)
; #define PG8_LDA(dst, b, h) do { _Pragma("unroll") for (int m = 0; m < 4; ++m) _Pragma("unroll") for (int k = 0; k < 2; ++k) dst[m][k] = *(const LAS bf16x8*)(lds + PG8_SA(b, h) + aoff + m * 2048 + k * 1024); } while (0)
; #define PG8_MMA(ai, bj, At, Bt) do { __builtin_amdgcn_s_setprio(1); _Pragma("unroll") for (int m = 0; m < 4; ++m) _Pragma("unroll") for (int n = 0; n < 2; ++n) _Pragma("unroll") for (int k = 0; k < 2; ++k) \
;         acc[ai][bj][m][n] = __builtin_amdgcn_mfma_f32_16x16x32_bf16(Bt[n][k], At[m][k], acc[ai][bj][m][n], 0, 0, 0); __builtin_amdgcn_s_setprio(0); } while (0)
; #define PG8_WAIT_V(n) asm volatile("s_waitcnt vmcnt(" #n ")" ::: "memory")
; #define PG8_WAIT_L(n) asm volatile("s_waitcnt lgkmcnt(" #n ")" ::: "memory")
; #define PG8_BAR __builtin_amdgcn_s_barrier()
; #define PG8_SCHED __builtin_amdgcn_sched_barrier(0)
; template <class Epi, class Sched = StaticOrder, class EpiSub = NoSub, bool FAST = false>
; __device__ __forceinline__ void gemm_phase(LAS unsigned char* lds, const Gemm g, const Sched& S, const Epi& E, const EpiSub& ES = EpiSub()) {
;     ...
;             PG8_LDA(At, 1, 1); PG8_STAGE(PG8_SB(1, 0), b3, voffB); PG8_STAGE(PG8_SB(1, 1), b3 + hstepB, voffB); PG8_STAGE(PG8_SA(1, 0), a3, voffA);
;             PG8_WAIT_V(8); PG8_WAIT_L(0); PG8_BAR; PG8_MMA(1, 0, At, B0); PG8_MMA(1, 1, At, B1); PG8_BAR; PG8_SCHED;
;     ...
;         if constexpr (FAST && PG8_ALIGN) { if (wr == 0) PG8_BAR; }
	s_add_i32 s42, s73, s17
	v_lshl_add_u64 v[208:209], v[208:209], 0, s[12:13]
	s_mov_b32 m0, s42
	ds_read_b128 v[160:163], v217 offset:49152
	ds_read_b128 v[164:167], v217 offset:50176
	ds_read_b128 v[168:171], v217 offset:51200
	ds_read_b128 v[172:175], v217 offset:52224
	ds_read_b128 v[176:179], v217 offset:53248
	ds_read_b128 v[180:183], v217 offset:54272
	ds_read_b128 v[200:203], v217 offset:55296
	ds_read_b128 v[204:207], v217 offset:56320
	global_load_lds_dwordx4 v[208:209], off
	s_add_i32 m0, s42, 0x2000
	s_add_u32 s40, s40, 0x80080
	v_lshl_add_u64 v[208:209], v[210:211], 0, s[12:13]
	s_addc_u32 s41, s41, 0
	s_add_i32 s42, s76, s17
	global_load_lds_dwordx4 v[208:209], off
	v_lshl_add_u64 v[208:209], s[40:41], 0, v[186:187]
	s_mov_b32 m0, s42
	s_nop 0
	global_load_lds_dwordx4 v[208:209], off
	v_lshl_add_u64 v[208:209], s[40:41], 0, v[190:191]
	s_add_i32 m0, s42, 0x2000
	s_nop 0
	global_load_lds_dwordx4 v[208:209], off
	v_lshl_add_u64 v[208:209], v[218:219], 0, s[12:13]
	s_mov_b32 m0, s55
	s_nop 0
	global_load_lds_dwordx4 v[208:209], off
	v_lshl_add_u64 v[208:209], v[220:221], 0, s[12:13]
	s_mov_b32 m0, s56
	s_nop 0
	global_load_lds_dwordx4 v[208:209], off
	s_waitcnt vmcnt(8)
	s_waitcnt lgkmcnt(0)
	s_barrier
	s_setprio 1
	v_mfma_f32_16x16x32_bf16 v[60:63], v[96:99], v[160:163], v[60:63]
	v_mfma_f32_16x16x32_bf16 v[56:59], v[112:115], v[160:163], v[56:59]
	v_mfma_f32_16x16x32_bf16 v[44:47], v[96:99], v[168:171], v[44:47]
	v_mfma_f32_16x16x32_bf16 v[40:43], v[112:115], v[168:171], v[40:43]
	v_mfma_f32_16x16x32_bf16 v[28:31], v[96:99], v[176:179], v[28:31]
	v_mfma_f32_16x16x32_bf16 v[24:27], v[112:115], v[176:179], v[24:27]
	v_mfma_f32_16x16x32_bf16 v[12:15], v[96:99], v[200:203], v[12:15]
	v_mfma_f32_16x16x32_bf16 v[8:11], v[112:115], v[200:203], v[8:11]
	v_mfma_f32_16x16x32_bf16 v[60:63], v[100:103], v[164:167], v[60:63]
	v_mfma_f32_16x16x32_bf16 v[56:59], v[116:119], v[164:167], v[56:59]
	v_mfma_f32_16x16x32_bf16 v[44:47], v[100:103], v[172:175], v[44:47]
	v_mfma_f32_16x16x32_bf16 v[40:43], v[116:119], v[172:175], v[40:43]
	v_mfma_f32_16x16x32_bf16 v[28:31], v[100:103], v[180:183], v[28:31]
	v_mfma_f32_16x16x32_bf16 v[24:27], v[116:119], v[180:183], v[24:27]
	v_mfma_f32_16x16x32_bf16 v[12:15], v[100:103], v[204:207], v[12:15]
	v_mfma_f32_16x16x32_bf16 v[8:11], v[116:119], v[204:207], v[8:11]
	s_setprio 0
	s_setprio 1
	v_mfma_f32_16x16x32_bf16 v[52:55], v[144:147], v[160:163], v[52:55]
	v_mfma_f32_16x16x32_bf16 v[48:51], v[152:155], v[160:163], v[48:51]
	v_mfma_f32_16x16x32_bf16 v[36:39], v[144:147], v[168:171], v[36:39]
	v_mfma_f32_16x16x32_bf16 v[32:35], v[152:155], v[168:171], v[32:35]
	v_mfma_f32_16x16x32_bf16 v[20:23], v[144:147], v[176:179], v[20:23]
	v_mfma_f32_16x16x32_bf16 v[16:19], v[152:155], v[176:179], v[16:19]
	v_mfma_f32_16x16x32_bf16 v[4:7], v[144:147], v[200:203], v[4:7]
	v_mfma_f32_16x16x32_bf16 v[0:3], v[152:155], v[200:203], v[0:3]
	v_mfma_f32_16x16x32_bf16 v[52:55], v[148:151], v[164:167], v[52:55]
	v_mfma_f32_16x16x32_bf16 v[48:51], v[156:159], v[164:167], v[48:51]
	v_mfma_f32_16x16x32_bf16 v[36:39], v[148:151], v[172:175], v[36:39]
	v_mfma_f32_16x16x32_bf16 v[32:35], v[156:159], v[172:175], v[32:35]
	v_mfma_f32_16x16x32_bf16 v[20:23], v[148:151], v[180:183], v[20:23]
	v_mfma_f32_16x16x32_bf16 v[16:19], v[156:159], v[180:183], v[16:19]
	v_mfma_f32_16x16x32_bf16 v[4:7], v[148:151], v[204:207], v[4:7]
	v_mfma_f32_16x16x32_bf16 v[0:3], v[156:159], v[204:207], v[0:3]
	s_setprio 0
	s_barrier
	s_add_u32 s38, s38, 0x100
	s_addc_u32 s39, s39, 0
	s_add_u32 s70, s70, 0x100
	s_addc_u32 s71, s71, 0
	s_cmp_ge_u32 s72, s29
	s_mov_b32 s42, s72
	s_cbranch_scc0 .LBB0_769
	s_and_b64 vcc, exec, s[14:15]
	s_cbranch_vccz .LBB0_772
	s_barrier

; #define PG8_STAGE(bufoff, gbase, voff) do { _Pragma("unroll") for (int _i = 0; _i < 2; ++_i) \
;         __builtin_amdgcn_global_load_lds((const unsigned*)((const char*)(gbase) + (voff)[_i]), (LAS unsigned*)(lds + (bufoff) + ldsw + _i * 8192), 16, 0, 0); } while (0)
; #define PG8_LDA(dst, b, h) do { _Pragma("unroll") for (int m = 0; m < 4; ++m) _Pragma("unroll") for (int k = 0; k < 2; ++k) dst[m][k] = *(const LAS bf16x8*)(lds + PG8_SA(b, h) + aoff + m * 2048 + k * 1024); } while (0)
; #define PG8_LDB(dst, b, h) do { _Pragma("unroll") for (int n = 0; n < 2; ++n) _Pragma("unroll") for (int k = 0; k < 2; ++k) dst[n][k] = *(const LAS bf16x8*)(lds + PG8_SB(b, h) + boff + n * 2048 + k * 1024); } while (0)
; #define PG8_WAIT_V(n) asm volatile("s_waitcnt vmcnt(" #n ")" ::: "memory")
; #define PG8_BAR __builtin_amdgcn_s_barrier()
; template <class Epi, class Sched = StaticOrder, class EpiSub = NoSub, bool FAST = false>
; __device__ __forceinline__ void gemm_phase(LAS unsigned char* lds, const Gemm g, const Sched& S, const Epi& E, const EpiSub& ES = EpiSub()) {
;     ...
;         const bool has_next = S.next(ui + 1, nxt);
;         const size_t nko = (has_next && nxt.kb >= 0) ? nxt.kb * ksubB : 0;
;         const char* nA = has_next ? (const char*)g.A + (size_t)nxt.pm * tstepA + (size_t)nxt.pn * g.acs + nko : cA; const char* nB = has_next ? (const char*)g.Bt + (size_t)nxt.pn * tstepB + nko : cB;
;         const int nt = cur.kb < 0 ? ntMain : ntSub;
;         for (int t = 0; t < nt; t += 2) {
;             const bool last = (t == nt - 2);
;             const char* a1 = cA + (size_t)(t + 1) * kstep;
;             const char* a2 = last ? nA : cA + (size_t)(t + 2) * kstep; const char* b2 = last ? nB : cB + (size_t)(t + 2) * kstep;
;             const char* a3 = a2 + kstep; const char* b3 = b2 + kstep;
;             if constexpr (FAST && PG8_SP2) {
;             PG8_LDB(B0, 0, 0); PG8_LDB(B1, 0, 1); PG8_SCHED; PG8_LDA(At, 0, 0); PG8_STAGE(PG8_SA(1, 1), a1 + hstepA, voffA);
;             PG8_WAIT_V(8); PG8_WAIT_L(0); PG8_BAR; PG8_MMA(0, 0, At, B0); PG8_MMA(0, 1, At, B1); PG8_BAR; PG8_SCHED;
;             PG8_LDA(At, 0, 1); PG8_STAGE(PG8_SB(0, 0), b2, voffB); PG8_STAGE(PG8_SB(0, 1), b2 + hstepB, voffB); PG8_STAGE(PG8_SA(0, 0), a2, voffA);
;             PG8_WAIT_V(8); PG8_WAIT_L(0); PG8_BAR; PG8_MMA(1, 0, At, B0); PG8_MMA(1, 1, At, B1); PG8_BAR; PG8_SCHED;
.LBB0_985:
	ds_read_b128 v[150:153], v147
	ds_read_b128 v[154:157], v147 offset:1024
	ds_read_b128 v[158:161], v147 offset:2048
	ds_read_b128 v[162:165], v147 offset:3072
	ds_read_b128 v[166:169], v148
	ds_read_b128 v[170:173], v148 offset:1024
	ds_read_b128 v[174:177], v148 offset:2048
	ds_read_b128 v[178:181], v148 offset:3072
	s_add_u32 s24, s22, 0xfff80080
	s_addc_u32 s25, s23, -1
	s_cmp_eq_u32 s49, 28
	s_cselect_b32 s27, s15, s25
	s_cselect_b32 s26, s45, s24
	s_cselect_b32 s25, s13, s48
	s_cselect_b32 s24, s46, s47
	v_lshl_add_u64 v[190:191], s[22:23], 0, v[136:137]
	s_add_i32 m0, s21, 0xc000
	ds_read_b128 v[182:185], v149
	ds_read_b128 v[186:189], v149 offset:1024
	ds_read_b128 v[194:197], v149 offset:2048
	ds_read_b128 v[198:201], v149 offset:3072
	ds_read_b128 v[202:205], v149 offset:4096
	ds_read_b128 v[206:209], v149 offset:5120
	ds_read_b128 v[210:213], v149 offset:6144
	ds_read_b128 v[214:217], v149 offset:7168
	global_load_lds_dwordx4 v[190:191], off
	v_lshl_add_u64 v[190:191], s[22:23], 0, v[138:139]
	s_add_i32 m0, s21, 0xe000
	s_nop 0
	global_load_lds_dwordx4 v[190:191], off
	s_waitcnt vmcnt(8)
	s_waitcnt lgkmcnt(0)
	s_barrier
	s_setprio 1
	v_mfma_f32_16x16x32_bf16 v[124:127], v[150:153], v[182:185], v[124:127]
	v_mfma_f32_16x16x32_bf16 v[116:119], v[158:161], v[182:185], v[116:119]
	v_mfma_f32_16x16x32_bf16 v[108:111], v[150:153], v[194:197], v[108:111]
	v_mfma_f32_16x16x32_bf16 v[100:103], v[158:161], v[194:197], v[100:103]
	v_mfma_f32_16x16x32_bf16 v[92:95], v[150:153], v[202:205], v[92:95]
	v_mfma_f32_16x16x32_bf16 v[84:87], v[158:161], v[202:205], v[84:87]
	v_mfma_f32_16x16x32_bf16 v[76:79], v[150:153], v[210:213], v[76:79]
	v_mfma_f32_16x16x32_bf16 v[68:71], v[158:161], v[210:213], v[68:71]
	v_mfma_f32_16x16x32_bf16 v[124:127], v[154:157], v[186:189], v[124:127]
	v_mfma_f32_16x16x32_bf16 v[116:119], v[162:165], v[186:189], v[116:119]
	v_mfma_f32_16x16x32_bf16 v[108:111], v[154:157], v[198:201], v[108:111]
	v_mfma_f32_16x16x32_bf16 v[100:103], v[162:165], v[198:201], v[100:103]
	v_mfma_f32_16x16x32_bf16 v[92:95], v[154:157], v[206:209], v[92:95]
	v_mfma_f32_16x16x32_bf16 v[84:87], v[162:165], v[206:209], v[84:87]
	v_mfma_f32_16x16x32_bf16 v[76:79], v[154:157], v[214:217], v[76:79]
	v_mfma_f32_16x16x32_bf16 v[68:71], v[162:165], v[214:217], v[68:71]
	s_setprio 0
	s_setprio 1
	v_mfma_f32_16x16x32_bf16 v[120:123], v[166:169], v[182:185], v[120:123]
	v_mfma_f32_16x16x32_bf16 v[112:115], v[174:177], v[182:185], v[112:115]
	v_mfma_f32_16x16x32_bf16 v[104:107], v[166:169], v[194:197], v[104:107]
	v_mfma_f32_16x16x32_bf16 v[96:99], v[174:177], v[194:197], v[96:99]
	v_mfma_f32_16x16x32_bf16 v[88:91], v[166:169], v[202:205], v[88:91]
	v_mfma_f32_16x16x32_bf16 v[80:83], v[174:177], v[202:205], v[80:83]
	v_mfma_f32_16x16x32_bf16 v[72:75], v[166:169], v[210:213], v[72:75]
	v_mfma_f32_16x16x32_bf16 v[64:67], v[174:177], v[210:213], v[64:67]
	v_mfma_f32_16x16x32_bf16 v[120:123], v[170:173], v[186:189], v[120:123]
	v_mfma_f32_16x16x32_bf16 v[112:115], v[178:181], v[186:189], v[112:115]
	v_mfma_f32_16x16x32_bf16 v[104:107], v[170:173], v[198:201], v[104:107]
	v_mfma_f32_16x16x32_bf16 v[96:99], v[178:181], v[198:201], v[96:99]
	v_mfma_f32_16x16x32_bf16 v[88:91], v[170:173], v[206:209], v[88:91]
	v_mfma_f32_16x16x32_bf16 v[80:83], v[178:181], v[206:209], v[80:83]
	v_mfma_f32_16x16x32_bf16 v[72:75], v[170:173], v[214:217], v[72:75]
	v_mfma_f32_16x16x32_bf16 v[64:67], v[178:181], v[214:217], v[64:67]
	s_setprio 0
	s_barrier
	s_add_i32 s50, s42, s28
	v_lshl_add_u64 v[190:191], s[24:25], 0, v[130:131]
	s_mov_b32 m0, s50
	ds_read_b128 v[182:185], v149 offset:16384
	ds_read_b128 v[186:189], v149 offset:17408
	ds_read_b128 v[194:197], v149 offset:18432
	ds_read_b128 v[198:201], v149 offset:19456
	ds_read_b128 v[202:205], v149 offset:20480
	ds_read_b128 v[206:209], v149 offset:21504
	ds_read_b128 v[210:213], v149 offset:22528
	ds_read_b128 v[214:217], v149 offset:23552
	global_load_lds_dwordx4 v[190:191], off
	s_add_i32 m0, s50, 0x2000
	s_add_u32 s50, s24, 0x80000
	v_lshl_add_u64 v[218:219], s[24:25], 0, v[134:135]
	s_addc_u32 s51, s25, 0
	s_add_i32 s52, s43, s28
	global_load_lds_dwordx4 v[218:219], off
	v_lshl_add_u64 v[220:221], s[50:51], 0, v[130:131]
	s_mov_b32 m0, s52
	v_lshl_add_u64 v[222:223], s[26:27], 0, v[132:133]
	global_load_lds_dwordx4 v[220:221], off
	v_lshl_add_u64 v[220:221], s[50:51], 0, v[134:135]
	s_add_i32 m0, s52, 0x2000
	s_nop 0
	global_load_lds_dwordx4 v[220:221], off
	v_lshl_add_u64 v[220:221], s[26:27], 0, v[128:129]
	s_mov_b32 m0, s21
	s_nop 0
	global_load_lds_dwordx4 v[220:221], off
	s_mov_b32 m0, s31
	s_nop 0
	global_load_lds_dwordx4 v[222:223], off
	s_waitcnt vmcnt(8)
	s_waitcnt lgkmcnt(0)
	s_barrier
; #define PG8_STAGE(bufoff, gbase, voff) do { _Pragma("unroll") for (int _i = 0; _i < 2; ++_i) \
;         __builtin_amdgcn_global_load_lds((const unsigned*)((const char*)(gbase) + (voff)[_i]), (LAS unsigned*)(lds + (bufoff) + ldsw + _i * 8192), 16, 0, 0); } while (0)
; #define PG8_LDA(dst, b, h) do { _Pragma("unroll") for (int m = 0; m < 4; ++m) _Pragma("unroll") for (int k = 0; k < 2; ++k) dst[m][k] = *(const LAS bf16x8*)(lds + PG8_SA(b, h) + aoff + m * 2048 + k * 1024); } while (0)
; #define PG8_LDB(dst, b, h) do { _Pragma("unroll") for (int n = 0; n < 2; ++n) _Pragma("unroll") for (int k = 0; k < 2; ++k) dst[n][k] = *(const LAS bf16x8*)(lds + PG8_SB(b, h) + boff + n * 2048 + k * 1024); } while (0)
; #define PG8_MMA(ai, bj, At, Bt) do { __builtin_amdgcn_s_setprio(1); _Pragma("unroll") for (int m = 0; m < 4; ++m) _Pragma("unroll") for (int n = 0; n < 2; ++n) _Pragma("unroll") for (int k = 0; k < 2; ++k) \
;         acc[ai][bj][m][n] = __builtin_amdgcn_mfma_f32_16x16x32_bf16(Bt[n][k], At[m][k], acc[ai][bj][m][n], 0, 0, 0); __builtin_amdgcn_s_setprio(0); } while (0)
; #define PG8_WAIT_V(n) asm volatile("s_waitcnt vmcnt(" #n ")" ::: "memory")
; #define PG8_WAIT_L(n) asm volatile("s_waitcnt lgkmcnt(" #n ")" ::: "memory")
; #define PG8_BAR __builtin_amdgcn_s_barrier()
; #define PG8_SCHED __builtin_amdgcn_sched_barrier(0)
; template <class Epi, class Sched = StaticOrder, class EpiSub = NoSub, bool FAST = false>
; __device__ __forceinline__ void gemm_phase(LAS unsigned char* lds, const Gemm g, const Sched& S, const Epi& E, const EpiSub& ES = EpiSub()) {
;     ...
;             PG8_WAIT_V(8); PG8_WAIT_L(0); PG8_BAR; PG8_MMA(1, 0, At, B0); PG8_MMA(1, 1, At, B1); PG8_BAR; PG8_SCHED;
;             PG8_LDB(B0, 1, 0); PG8_LDB(B1, 1, 1); PG8_SCHED; PG8_LDA(At, 1, 0); PG8_STAGE(PG8_SA(0, 1), a2 + hstepA, voffA);
;             PG8_WAIT_V(8); PG8_WAIT_L(0); PG8_BAR; PG8_MMA(0, 0, At, B0); PG8_MMA(0, 1, At, B1); PG8_BAR; PG8_SCHED;
	s_setprio 1
	v_mfma_f32_16x16x32_bf16 v[60:63], v[150:153], v[182:185], v[60:63]
	v_mfma_f32_16x16x32_bf16 v[52:55], v[158:161], v[182:185], v[52:55]
	v_mfma_f32_16x16x32_bf16 v[44:47], v[150:153], v[194:197], v[44:47]
	v_mfma_f32_16x16x32_bf16 v[36:39], v[158:161], v[194:197], v[36:39]
	v_mfma_f32_16x16x32_bf16 v[28:31], v[150:153], v[202:205], v[28:31]
	v_mfma_f32_16x16x32_bf16 v[20:23], v[158:161], v[202:205], v[20:23]
	v_mfma_f32_16x16x32_bf16 v[12:15], v[150:153], v[210:213], v[12:15]
	v_mfma_f32_16x16x32_bf16 v[4:7], v[158:161], v[210:213], v[4:7]
	v_mfma_f32_16x16x32_bf16 v[60:63], v[154:157], v[186:189], v[60:63]
	v_mfma_f32_16x16x32_bf16 v[52:55], v[162:165], v[186:189], v[52:55]
	v_mfma_f32_16x16x32_bf16 v[44:47], v[154:157], v[198:201], v[44:47]
	v_mfma_f32_16x16x32_bf16 v[36:39], v[162:165], v[198:201], v[36:39]
	v_mfma_f32_16x16x32_bf16 v[28:31], v[154:157], v[206:209], v[28:31]
	v_mfma_f32_16x16x32_bf16 v[20:23], v[162:165], v[206:209], v[20:23]
	v_mfma_f32_16x16x32_bf16 v[12:15], v[154:157], v[214:217], v[12:15]
	v_mfma_f32_16x16x32_bf16 v[4:7], v[162:165], v[214:217], v[4:7]
	s_setprio 0
	s_setprio 1
	v_mfma_f32_16x16x32_bf16 v[56:59], v[166:169], v[182:185], v[56:59]
	v_mfma_f32_16x16x32_bf16 v[48:51], v[174:177], v[182:185], v[48:51]
	v_mfma_f32_16x16x32_bf16 v[40:43], v[166:169], v[194:197], v[40:43]
	v_mfma_f32_16x16x32_bf16 v[32:35], v[174:177], v[194:197], v[32:35]
	v_mfma_f32_16x16x32_bf16 v[24:27], v[166:169], v[202:205], v[24:27]
	v_mfma_f32_16x16x32_bf16 v[16:19], v[174:177], v[202:205], v[16:19]
	v_mfma_f32_16x16x32_bf16 v[8:11], v[166:169], v[210:213], v[8:11]
	v_mfma_f32_16x16x32_bf16 v[0:3], v[174:177], v[210:213], v[0:3]
	v_mfma_f32_16x16x32_bf16 v[56:59], v[170:173], v[186:189], v[56:59]
	v_mfma_f32_16x16x32_bf16 v[48:51], v[178:181], v[186:189], v[48:51]
	v_mfma_f32_16x16x32_bf16 v[40:43], v[170:173], v[198:201], v[40:43]
	v_mfma_f32_16x16x32_bf16 v[32:35], v[178:181], v[198:201], v[32:35]
	v_mfma_f32_16x16x32_bf16 v[24:27], v[170:173], v[206:209], v[24:27]
	v_mfma_f32_16x16x32_bf16 v[16:19], v[178:181], v[206:209], v[16:19]
	v_mfma_f32_16x16x32_bf16 v[8:11], v[170:173], v[214:217], v[8:11]
	v_mfma_f32_16x16x32_bf16 v[0:3], v[178:181], v[214:217], v[0:3]
	s_setprio 0
	s_barrier
	s_add_i32 s50, 0, 0x18000
	s_add_i32 s51, 0, 0x1c000
	v_add_u32_e32 v162, s50, v145
	v_add_u32_e32 v178, s51, v145
	ds_read_b128 v[150:153], v162
	ds_read_b128 v[154:157], v162 offset:1024
	ds_read_b128 v[158:161], v162 offset:2048
	ds_read_b128 v[162:165], v162 offset:3072
	ds_read_b128 v[166:169], v178
	ds_read_b128 v[170:173], v178 offset:1024
	ds_read_b128 v[174:177], v178 offset:2048
	ds_read_b128 v[178:181], v178 offset:3072
	s_add_u32 s26, s26, 0x80000
	s_addc_u32 s27, s27, 0
	s_mov_b32 m0, s36
	v_lshl_add_u64 v[224:225], s[26:27], 0, v[128:129]
	ds_read_b128 v[182:185], v149 offset:32768
	ds_read_b128 v[186:189], v149 offset:33792
	ds_read_b128 v[194:197], v149 offset:34816
	ds_read_b128 v[198:201], v149 offset:35840
	ds_read_b128 v[202:205], v149 offset:36864
	ds_read_b128 v[206:209], v149 offset:37888
	ds_read_b128 v[210:213], v149 offset:38912
	ds_read_b128 v[214:217], v149 offset:39936
	global_load_lds_dwordx4 v[224:225], off
	v_lshl_add_u64 v[224:225], s[26:27], 0, v[132:133]
	s_mov_b32 m0, s37
	s_nop 0
	global_load_lds_dwordx4 v[224:225], off
	s_waitcnt vmcnt(8)
	s_waitcnt lgkmcnt(0)
	s_barrier
	s_setprio 1
	v_mfma_f32_16x16x32_bf16 v[124:127], v[150:153], v[182:185], v[124:127]
	v_mfma_f32_16x16x32_bf16 v[116:119], v[158:161], v[182:185], v[116:119]
	v_mfma_f32_16x16x32_bf16 v[108:111], v[150:153], v[194:197], v[108:111]
	v_mfma_f32_16x16x32_bf16 v[100:103], v[158:161], v[194:197], v[100:103]
	v_mfma_f32_16x16x32_bf16 v[92:95], v[150:153], v[202:205], v[92:95]
	v_mfma_f32_16x16x32_bf16 v[84:87], v[158:161], v[202:205], v[84:87]
	v_mfma_f32_16x16x32_bf16 v[76:79], v[150:153], v[210:213], v[76:79]
	v_mfma_f32_16x16x32_bf16 v[68:71], v[158:161], v[210:213], v[68:71]
	v_mfma_f32_16x16x32_bf16 v[124:127], v[154:157], v[186:189], v[124:127]
	v_mfma_f32_16x16x32_bf16 v[116:119], v[162:165], v[186:189], v[116:119]
	v_mfma_f32_16x16x32_bf16 v[108:111], v[154:157], v[198:201], v[108:111]
	v_mfma_f32_16x16x32_bf16 v[100:103], v[162:165], v[198:201], v[100:103]
	v_mfma_f32_16x16x32_bf16 v[92:95], v[154:157], v[206:209], v[92:95]
	v_mfma_f32_16x16x32_bf16 v[84:87], v[162:165], v[206:209], v[84:87]
	v_mfma_f32_16x16x32_bf16 v[76:79], v[154:157], v[214:217], v[76:79]
	v_mfma_f32_16x16x32_bf16 v[68:71], v[162:165], v[214:217], v[68:71]
	s_setprio 0
	s_setprio 1
	v_mfma_f32_16x16x32_bf16 v[120:123], v[166:169], v[182:185], v[120:123]
	v_mfma_f32_16x16x32_bf16 v[112:115], v[174:177], v[182:185], v[112:115]
	v_mfma_f32_16x16x32_bf16 v[104:107], v[166:169], v[194:197], v[104:107]
	v_mfma_f32_16x16x32_bf16 v[96:99], v[174:177], v[194:197], v[96:99]
	v_mfma_f32_16x16x32_bf16 v[88:91], v[166:169], v[202:205], v[88:91]
	v_mfma_f32_16x16x32_bf16 v[80:83], v[174:177], v[202:205], v[80:83]
	v_mfma_f32_16x16x32_bf16 v[72:75], v[166:169], v[210:213], v[72:75]
	v_mfma_f32_16x16x32_bf16 v[64:67], v[174:177], v[210:213], v[64:67]
	v_mfma_f32_16x16x32_bf16 v[120:123], v[170:173], v[186:189], v[120:123]
	v_mfma_f32_16x16x32_bf16 v[112:115], v[178:181], v[186:189], v[112:115]
	v_mfma_f32_16x16x32_bf16 v[104:107], v[170:173], v[198:201], v[104:107]
	v_mfma_f32_16x16x32_bf16 v[96:99], v[178:181], v[198:201], v[96:99]
	v_mfma_f32_16x16x32_bf16 v[88:91], v[170:173], v[206:209], v[88:91]
	v_mfma_f32_16x16x32_bf16 v[80:83], v[178:181], v[206:209], v[80:83]
	v_mfma_f32_16x16x32_bf16 v[72:75], v[170:173], v[214:217], v[72:75]
	v_mfma_f32_16x16x32_bf16 v[64:67], v[178:181], v[214:217], v[64:67]
	s_setprio 0
	s_barrier
; #define PG8_STAGE(bufoff, gbase, voff) do { _Pragma("unroll") for (int _i = 0; _i < 2; ++_i) \
;         __builtin_amdgcn_global_load_lds((const unsigned*)((const char*)(gbase) + (voff)[_i]), (LAS unsigned*)(lds + (bufoff) + ldsw + _i * 8192), 16, 0, 0); } while (0)
; #define PG8_LDA(dst, b, h) do { _Pragma("unroll") for (int m = 0; m < 4; ++m) _Pragma("unroll") for (int k = 0; k < 2; ++k) dst[m][k] = *(const LAS bf16x8*)(lds + PG8_SA(b, h) + aoff + m * 2048 + k * 1024); } while (0)
; #define PG8_MMA(ai, bj, At, Bt) do { __builtin_amdgcn_s_setprio(1); _Pragma("unroll") for (int m = 0; m < 4; ++m) _Pragma("unroll") for (int n = 0; n < 2; ++n) _Pragma("unroll") for (int k = 0; k < 2; ++k) \
;         acc[ai][bj][m][n] = __builtin_amdgcn_mfma_f32_16x16x32_bf16(Bt[n][k], At[m][k], acc[ai][bj][m][n], 0, 0, 0); __builtin_amdgcn_s_setprio(0); } while (0)
; #define PG8_WAIT_V(n) asm volatile("s_waitcnt vmcnt(" #n ")" ::: "memory")
; #define PG8_WAIT_L(n) asm volatile("s_waitcnt lgkmcnt(" #n ")" ::: "memory")
; #define PG8_BAR __builtin_amdgcn_s_barrier()
; #define PG8_SCHED __builtin_amdgcn_sched_barrier(0)
; template <class Epi, class Sched = StaticOrder, class EpiSub = NoSub, bool FAST = false>
; __device__ __forceinline__ void gemm_phase(LAS unsigned char* lds, const Gemm g, const Sched& S, const Epi& E, const EpiSub& ES = EpiSub()) {
;     ...
;             PG8_LDA(At, 1, 1); PG8_STAGE(PG8_SB(1, 0), b3, voffB); PG8_STAGE(PG8_SB(1, 1), b3 + hstepB, voffB); PG8_STAGE(PG8_SA(1, 0), a3, voffA);
;             PG8_WAIT_V(8); PG8_WAIT_L(0); PG8_BAR; PG8_MMA(1, 0, At, B0); PG8_MMA(1, 1, At, B1); PG8_BAR; PG8_SCHED;
;     ...
;         if constexpr (FAST && PG8_ALIGN) { if (wr == 0) PG8_BAR; }
	s_add_i32 s26, s50, s28
	v_lshl_add_u64 v[190:191], v[190:191], 0, s[8:9]
	s_mov_b32 m0, s26
	ds_read_b128 v[182:185], v149 offset:49152
	ds_read_b128 v[186:189], v149 offset:50176
	ds_read_b128 v[194:197], v149 offset:51200
	ds_read_b128 v[198:201], v149 offset:52224
	ds_read_b128 v[202:205], v149 offset:53248
	ds_read_b128 v[206:209], v149 offset:54272
	ds_read_b128 v[210:213], v149 offset:55296
	ds_read_b128 v[214:217], v149 offset:56320
	global_load_lds_dwordx4 v[190:191], off
	s_add_i32 m0, s26, 0x2000
	s_add_u32 s24, s24, 0x80080
	v_lshl_add_u64 v[190:191], v[218:219], 0, s[8:9]
	s_addc_u32 s25, s25, 0
	s_add_i32 s26, s51, s28
	global_load_lds_dwordx4 v[190:191], off
	v_lshl_add_u64 v[190:191], s[24:25], 0, v[130:131]
	s_mov_b32 m0, s26
	s_nop 0
	global_load_lds_dwordx4 v[190:191], off
	v_lshl_add_u64 v[190:191], s[24:25], 0, v[134:135]
	s_add_i32 m0, s26, 0x2000
	s_nop 0
	global_load_lds_dwordx4 v[190:191], off
	v_lshl_add_u64 v[190:191], v[220:221], 0, s[8:9]
	s_mov_b32 m0, s40
	s_nop 0
	global_load_lds_dwordx4 v[190:191], off
	v_lshl_add_u64 v[190:191], v[222:223], 0, s[8:9]
	s_mov_b32 m0, s41
	s_nop 0
	global_load_lds_dwordx4 v[190:191], off
	s_waitcnt vmcnt(8)
	s_waitcnt lgkmcnt(0)
	s_barrier
	s_setprio 1
	v_mfma_f32_16x16x32_bf16 v[60:63], v[150:153], v[182:185], v[60:63]
	v_mfma_f32_16x16x32_bf16 v[52:55], v[158:161], v[182:185], v[52:55]
	v_mfma_f32_16x16x32_bf16 v[44:47], v[150:153], v[194:197], v[44:47]
	v_mfma_f32_16x16x32_bf16 v[36:39], v[158:161], v[194:197], v[36:39]
	v_mfma_f32_16x16x32_bf16 v[28:31], v[150:153], v[202:205], v[28:31]
	v_mfma_f32_16x16x32_bf16 v[20:23], v[158:161], v[202:205], v[20:23]
	v_mfma_f32_16x16x32_bf16 v[12:15], v[150:153], v[210:213], v[12:15]
	v_mfma_f32_16x16x32_bf16 v[4:7], v[158:161], v[210:213], v[4:7]
	v_mfma_f32_16x16x32_bf16 v[60:63], v[154:157], v[186:189], v[60:63]
	v_mfma_f32_16x16x32_bf16 v[52:55], v[162:165], v[186:189], v[52:55]
	v_mfma_f32_16x16x32_bf16 v[44:47], v[154:157], v[198:201], v[44:47]
	v_mfma_f32_16x16x32_bf16 v[36:39], v[162:165], v[198:201], v[36:39]
	v_mfma_f32_16x16x32_bf16 v[28:31], v[154:157], v[206:209], v[28:31]
	v_mfma_f32_16x16x32_bf16 v[20:23], v[162:165], v[206:209], v[20:23]
	v_mfma_f32_16x16x32_bf16 v[12:15], v[154:157], v[214:217], v[12:15]
	v_mfma_f32_16x16x32_bf16 v[4:7], v[162:165], v[214:217], v[4:7]
	s_setprio 0
	s_setprio 1
	v_mfma_f32_16x16x32_bf16 v[56:59], v[166:169], v[182:185], v[56:59]
	v_mfma_f32_16x16x32_bf16 v[48:51], v[174:177], v[182:185], v[48:51]
	v_mfma_f32_16x16x32_bf16 v[40:43], v[166:169], v[194:197], v[40:43]
	v_mfma_f32_16x16x32_bf16 v[32:35], v[174:177], v[194:197], v[32:35]
	v_mfma_f32_16x16x32_bf16 v[24:27], v[166:169], v[202:205], v[24:27]
	v_mfma_f32_16x16x32_bf16 v[16:19], v[174:177], v[202:205], v[16:19]
	v_mfma_f32_16x16x32_bf16 v[8:11], v[166:169], v[210:213], v[8:11]
	v_mfma_f32_16x16x32_bf16 v[0:3], v[174:177], v[210:213], v[0:3]
	v_mfma_f32_16x16x32_bf16 v[56:59], v[170:173], v[186:189], v[56:59]
	v_mfma_f32_16x16x32_bf16 v[48:51], v[178:181], v[186:189], v[48:51]
	v_mfma_f32_16x16x32_bf16 v[40:43], v[170:173], v[198:201], v[40:43]
	v_mfma_f32_16x16x32_bf16 v[32:35], v[178:181], v[198:201], v[32:35]
	v_mfma_f32_16x16x32_bf16 v[24:27], v[170:173], v[206:209], v[24:27]
	v_mfma_f32_16x16x32_bf16 v[16:19], v[178:181], v[206:209], v[16:19]
	v_mfma_f32_16x16x32_bf16 v[8:11], v[170:173], v[214:217], v[8:11]
	v_mfma_f32_16x16x32_bf16 v[0:3], v[178:181], v[214:217], v[0:3]
	s_setprio 0
	s_barrier
	s_add_i32 s49, s49, 2
	s_add_u32 s22, s22, 0x100
	s_addc_u32 s23, s23, 0
	s_add_u32 s47, s47, 0x100
	s_addc_u32 s48, s48, 0
	s_cmp_gt_u32 s49, 29
	s_cbranch_scc0 .LBB0_985
	s_and_b64 vcc, exec, s[10:11]
	s_cbranch_vccz .LBB0_988
	s_barrier

; #define PG8_STAGE(bufoff, gbase, voff) do { _Pragma("unroll") for (int _i = 0; _i < 2; ++_i) \
;         __builtin_amdgcn_global_load_lds((const unsigned*)((const char*)(gbase) + (voff)[_i]), (LAS unsigned*)(lds + (bufoff) + ldsw + _i * 8192), 16, 0, 0); } while (0)
; #define PG8_LDA(dst, b, h) do { _Pragma("unroll") for (int m = 0; m < 4; ++m) _Pragma("unroll") for (int k = 0; k < 2; ++k) dst[m][k] = *(const LAS bf16x8*)(lds + PG8_SA(b, h) + aoff + m * 2048 + k * 1024); } while (0)
; #define PG8_LDB(dst, b, h) do { _Pragma("unroll") for (int n = 0; n < 2; ++n) _Pragma("unroll") for (int k = 0; k < 2; ++k) dst[n][k] = *(const LAS bf16x8*)(lds + PG8_SB(b, h) + boff + n * 2048 + k * 1024); } while (0)
; #define PG8_WAIT_V(n) asm volatile("s_waitcnt vmcnt(" #n ")" ::: "memory")
; #define PG8_BAR __builtin_amdgcn_s_barrier()
; template <class Epi, class Sched = StaticOrder, class EpiSub = NoSub, bool FAST = false>
; __device__ __forceinline__ void gemm_phase(LAS unsigned char* lds, const Gemm g, const Sched& S, const Epi& E, const EpiSub& ES = EpiSub()) {
;     ...
;         const bool has_next = S.next(ui + 1, nxt);
;         const size_t nko = (has_next && nxt.kb >= 0) ? nxt.kb * ksubB : 0;
;         const char* nA = has_next ? (const char*)g.A + (size_t)nxt.pm * tstepA + (size_t)nxt.pn * g.acs + nko : cA; const char* nB = has_next ? (const char*)g.Bt + (size_t)nxt.pn * tstepB + nko : cB;
;         const int nt = cur.kb < 0 ? ntMain : ntSub;
;         for (int t = 0; t < nt; t += 2) {
;             const bool last = (t == nt - 2);
;             const char* a1 = cA + (size_t)(t + 1) * kstep;
;             const char* a2 = last ? nA : cA + (size_t)(t + 2) * kstep; const char* b2 = last ? nB : cB + (size_t)(t + 2) * kstep;
;             const char* a3 = a2 + kstep; const char* b3 = b2 + kstep;
;             if constexpr (FAST && PG8_SP2) {
;             PG8_LDB(B0, 0, 0); PG8_LDB(B1, 0, 1); PG8_SCHED; PG8_LDA(At, 0, 0); PG8_STAGE(PG8_SA(1, 1), a1 + hstepA, voffA);
;             PG8_WAIT_V(8); PG8_WAIT_L(0); PG8_BAR; PG8_MMA(0, 0, At, B0); PG8_MMA(0, 1, At, B1); PG8_BAR; PG8_SCHED;
;             PG8_LDA(At, 0, 1); PG8_STAGE(PG8_SB(0, 0), b2, voffB); PG8_STAGE(PG8_SB(0, 1), b2 + hstepB, voffB); PG8_STAGE(PG8_SA(0, 0), a2, voffA);
;             PG8_WAIT_V(8); PG8_WAIT_L(0); PG8_BAR; PG8_MMA(1, 0, At, B0); PG8_MMA(1, 1, At, B1); PG8_BAR; PG8_SCHED;
.LBB0_1079:
	ds_read_b128 v[96:99], v201
	ds_read_b128 v[100:103], v201 offset:1024
	ds_read_b128 v[108:111], v201 offset:2048
	ds_read_b128 v[116:119], v201 offset:3072
	ds_read_b128 v[144:147], v202
	ds_read_b128 v[148:151], v202 offset:1024
	ds_read_b128 v[152:155], v202 offset:2048
	ds_read_b128 v[156:159], v202 offset:3072
	s_add_i32 s85, s46, 2
	s_add_u32 s44, s42, 0xffea0080
	s_addc_u32 s45, s43, -1
	s_cmp_eq_u32 s71, s46
	s_cselect_b32 s46, s38, s44
	s_cselect_b32 s47, s39, s45
	s_cselect_b32 s45, s41, s84
	s_cselect_b32 s44, s40, s83
	v_lshl_add_u64 v[190:191], s[42:43], 0, v[176:177]
	s_add_i32 m0, s48, 0xc000
	ds_read_b128 v[160:163], v203
	ds_read_b128 v[164:167], v203 offset:1024
	ds_read_b128 v[182:185], v203 offset:2048
	ds_read_b128 v[186:189], v203 offset:3072
	ds_read_b128 v[194:197], v203 offset:4096
	ds_read_b128 v[204:207], v203 offset:5120
	ds_read_b128 v[208:211], v203 offset:6144
	ds_read_b128 v[212:215], v203 offset:7168
	global_load_lds_dwordx4 v[190:191], off
	v_lshl_add_u64 v[190:191], s[42:43], 0, v[178:179]
	s_add_i32 m0, s48, 0xe000
	s_nop 0
	global_load_lds_dwordx4 v[190:191], off
	s_waitcnt vmcnt(8)
	s_waitcnt lgkmcnt(0)
	s_barrier
	s_setprio 1
	v_mfma_f32_16x16x32_bf16 v[140:143], v[96:99], v[160:163], v[140:143]
	v_mfma_f32_16x16x32_bf16 v[136:139], v[108:111], v[160:163], v[136:139]
	v_mfma_f32_16x16x32_bf16 v[124:127], v[96:99], v[182:185], v[124:127]
	v_mfma_f32_16x16x32_bf16 v[120:123], v[108:111], v[182:185], v[120:123]
	v_mfma_f32_16x16x32_bf16 v[92:95], v[96:99], v[194:197], v[92:95]
	v_mfma_f32_16x16x32_bf16 v[88:91], v[108:111], v[194:197], v[88:91]
	v_mfma_f32_16x16x32_bf16 v[76:79], v[96:99], v[208:211], v[76:79]
	v_mfma_f32_16x16x32_bf16 v[72:75], v[108:111], v[208:211], v[72:75]
	v_mfma_f32_16x16x32_bf16 v[140:143], v[100:103], v[164:167], v[140:143]
	v_mfma_f32_16x16x32_bf16 v[136:139], v[116:119], v[164:167], v[136:139]
	v_mfma_f32_16x16x32_bf16 v[124:127], v[100:103], v[186:189], v[124:127]
	v_mfma_f32_16x16x32_bf16 v[120:123], v[116:119], v[186:189], v[120:123]
	v_mfma_f32_16x16x32_bf16 v[92:95], v[100:103], v[204:207], v[92:95]
	v_mfma_f32_16x16x32_bf16 v[88:91], v[116:119], v[204:207], v[88:91]
	v_mfma_f32_16x16x32_bf16 v[76:79], v[100:103], v[212:215], v[76:79]
	v_mfma_f32_16x16x32_bf16 v[72:75], v[116:119], v[212:215], v[72:75]
	s_setprio 0
	s_setprio 1
	v_mfma_f32_16x16x32_bf16 v[132:135], v[144:147], v[160:163], v[132:135]
	v_mfma_f32_16x16x32_bf16 v[128:131], v[152:155], v[160:163], v[128:131]
	v_mfma_f32_16x16x32_bf16 v[112:115], v[144:147], v[182:185], v[112:115]
	v_mfma_f32_16x16x32_bf16 v[104:107], v[152:155], v[182:185], v[104:107]
	v_mfma_f32_16x16x32_bf16 v[84:87], v[144:147], v[194:197], v[84:87]
	v_mfma_f32_16x16x32_bf16 v[80:83], v[152:155], v[194:197], v[80:83]
	v_mfma_f32_16x16x32_bf16 v[68:71], v[144:147], v[208:211], v[68:71]
	v_mfma_f32_16x16x32_bf16 v[64:67], v[152:155], v[208:211], v[64:67]
	v_mfma_f32_16x16x32_bf16 v[132:135], v[148:151], v[164:167], v[132:135]
	v_mfma_f32_16x16x32_bf16 v[128:131], v[156:159], v[164:167], v[128:131]
	v_mfma_f32_16x16x32_bf16 v[112:115], v[148:151], v[186:189], v[112:115]
	v_mfma_f32_16x16x32_bf16 v[104:107], v[156:159], v[186:189], v[104:107]
	v_mfma_f32_16x16x32_bf16 v[84:87], v[148:151], v[204:207], v[84:87]
	v_mfma_f32_16x16x32_bf16 v[80:83], v[156:159], v[204:207], v[80:83]
	v_mfma_f32_16x16x32_bf16 v[68:71], v[148:151], v[212:215], v[68:71]
	v_mfma_f32_16x16x32_bf16 v[64:67], v[156:159], v[212:215], v[64:67]
	s_setprio 0
	s_barrier
	s_add_i32 s86, s58, s27
	v_lshl_add_u64 v[190:191], s[44:45], 0, v[170:171]
	s_mov_b32 m0, s86
	ds_read_b128 v[160:163], v203 offset:16384
	ds_read_b128 v[164:167], v203 offset:17408
	ds_read_b128 v[182:185], v203 offset:18432
	ds_read_b128 v[186:189], v203 offset:19456
	ds_read_b128 v[194:197], v203 offset:20480
	ds_read_b128 v[204:207], v203 offset:21504
	ds_read_b128 v[208:211], v203 offset:22528
	ds_read_b128 v[212:215], v203 offset:23552
	global_load_lds_dwordx4 v[190:191], off
	s_add_i32 m0, s86, 0x2000
	s_add_u32 s86, s44, 0x160000
	v_lshl_add_u64 v[216:217], s[44:45], 0, v[174:175]
	s_addc_u32 s87, s45, 0
	s_add_i32 s88, s59, s27
	global_load_lds_dwordx4 v[216:217], off
	v_lshl_add_u64 v[218:219], s[86:87], 0, v[170:171]
	s_mov_b32 m0, s88
	v_lshl_add_u64 v[220:221], s[46:47], 0, v[172:173]
	global_load_lds_dwordx4 v[218:219], off
	v_lshl_add_u64 v[218:219], s[86:87], 0, v[174:175]
	s_add_i32 m0, s88, 0x2000
	s_nop 0
	global_load_lds_dwordx4 v[218:219], off
	v_lshl_add_u64 v[218:219], s[46:47], 0, v[168:169]
	s_mov_b32 m0, s48
	s_nop 0
	global_load_lds_dwordx4 v[218:219], off
	s_mov_b32 m0, s49
	s_nop 0
	global_load_lds_dwordx4 v[220:221], off
	s_waitcnt vmcnt(8)
	s_waitcnt lgkmcnt(0)
	s_barrier
; #define PG8_STAGE(bufoff, gbase, voff) do { _Pragma("unroll") for (int _i = 0; _i < 2; ++_i) \
;         __builtin_amdgcn_global_load_lds((const unsigned*)((const char*)(gbase) + (voff)[_i]), (LAS unsigned*)(lds + (bufoff) + ldsw + _i * 8192), 16, 0, 0); } while (0)
; #define PG8_LDA(dst, b, h) do { _Pragma("unroll") for (int m = 0; m < 4; ++m) _Pragma("unroll") for (int k = 0; k < 2; ++k) dst[m][k] = *(const LAS bf16x8*)(lds + PG8_SA(b, h) + aoff + m * 2048 + k * 1024); } while (0)
; #define PG8_LDB(dst, b, h) do { _Pragma("unroll") for (int n = 0; n < 2; ++n) _Pragma("unroll") for (int k = 0; k < 2; ++k) dst[n][k] = *(const LAS bf16x8*)(lds + PG8_SB(b, h) + boff + n * 2048 + k * 1024); } while (0)
; #define PG8_MMA(ai, bj, At, Bt) do { __builtin_amdgcn_s_setprio(1); _Pragma("unroll") for (int m = 0; m < 4; ++m) _Pragma("unroll") for (int n = 0; n < 2; ++n) _Pragma("unroll") for (int k = 0; k < 2; ++k) \
;         acc[ai][bj][m][n] = __builtin_amdgcn_mfma_f32_16x16x32_bf16(Bt[n][k], At[m][k], acc[ai][bj][m][n], 0, 0, 0); __builtin_amdgcn_s_setprio(0); } while (0)
; #define PG8_WAIT_V(n) asm volatile("s_waitcnt vmcnt(" #n ")" ::: "memory")
; #define PG8_WAIT_L(n) asm volatile("s_waitcnt lgkmcnt(" #n ")" ::: "memory")
; #define PG8_BAR __builtin_amdgcn_s_barrier()
; #define PG8_SCHED __builtin_amdgcn_sched_barrier(0)
; template <class Epi, class Sched = StaticOrder, class EpiSub = NoSub, bool FAST = false>
; __device__ __forceinline__ void gemm_phase(LAS unsigned char* lds, const Gemm g, const Sched& S, const Epi& E, const EpiSub& ES = EpiSub()) {
;     ...
;             PG8_WAIT_V(8); PG8_WAIT_L(0); PG8_BAR; PG8_MMA(1, 0, At, B0); PG8_MMA(1, 1, At, B1); PG8_BAR; PG8_SCHED;
;             PG8_LDB(B0, 1, 0); PG8_LDB(B1, 1, 1); PG8_SCHED; PG8_LDA(At, 1, 0); PG8_STAGE(PG8_SA(0, 1), a2 + hstepA, voffA);
;             PG8_WAIT_V(8); PG8_WAIT_L(0); PG8_BAR; PG8_MMA(0, 0, At, B0); PG8_MMA(0, 1, At, B1); PG8_BAR; PG8_SCHED;
	s_setprio 1
	v_mfma_f32_16x16x32_bf16 v[60:63], v[96:99], v[160:163], v[60:63]
	v_mfma_f32_16x16x32_bf16 v[56:59], v[108:111], v[160:163], v[56:59]
	v_mfma_f32_16x16x32_bf16 v[44:47], v[96:99], v[182:185], v[44:47]
	v_mfma_f32_16x16x32_bf16 v[40:43], v[108:111], v[182:185], v[40:43]
	v_mfma_f32_16x16x32_bf16 v[28:31], v[96:99], v[194:197], v[28:31]
	v_mfma_f32_16x16x32_bf16 v[24:27], v[108:111], v[194:197], v[24:27]
	v_mfma_f32_16x16x32_bf16 v[12:15], v[96:99], v[208:211], v[12:15]
	v_mfma_f32_16x16x32_bf16 v[8:11], v[108:111], v[208:211], v[8:11]
	v_mfma_f32_16x16x32_bf16 v[60:63], v[100:103], v[164:167], v[60:63]
	v_mfma_f32_16x16x32_bf16 v[56:59], v[116:119], v[164:167], v[56:59]
	v_mfma_f32_16x16x32_bf16 v[44:47], v[100:103], v[186:189], v[44:47]
	v_mfma_f32_16x16x32_bf16 v[40:43], v[116:119], v[186:189], v[40:43]
	v_mfma_f32_16x16x32_bf16 v[28:31], v[100:103], v[204:207], v[28:31]
	v_mfma_f32_16x16x32_bf16 v[24:27], v[116:119], v[204:207], v[24:27]
	v_mfma_f32_16x16x32_bf16 v[12:15], v[100:103], v[212:215], v[12:15]
	v_mfma_f32_16x16x32_bf16 v[8:11], v[116:119], v[212:215], v[8:11]
	s_setprio 0
	s_setprio 1
	v_mfma_f32_16x16x32_bf16 v[52:55], v[144:147], v[160:163], v[52:55]
	v_mfma_f32_16x16x32_bf16 v[48:51], v[152:155], v[160:163], v[48:51]
	v_mfma_f32_16x16x32_bf16 v[36:39], v[144:147], v[182:185], v[36:39]
	v_mfma_f32_16x16x32_bf16 v[32:35], v[152:155], v[182:185], v[32:35]
	v_mfma_f32_16x16x32_bf16 v[20:23], v[144:147], v[194:197], v[20:23]
	v_mfma_f32_16x16x32_bf16 v[16:19], v[152:155], v[194:197], v[16:19]
	v_mfma_f32_16x16x32_bf16 v[4:7], v[144:147], v[208:211], v[4:7]
	v_mfma_f32_16x16x32_bf16 v[0:3], v[152:155], v[208:211], v[0:3]
	v_mfma_f32_16x16x32_bf16 v[52:55], v[148:151], v[164:167], v[52:55]
	v_mfma_f32_16x16x32_bf16 v[48:51], v[156:159], v[164:167], v[48:51]
	v_mfma_f32_16x16x32_bf16 v[36:39], v[148:151], v[186:189], v[36:39]
	v_mfma_f32_16x16x32_bf16 v[32:35], v[156:159], v[186:189], v[32:35]
	v_mfma_f32_16x16x32_bf16 v[20:23], v[148:151], v[204:207], v[20:23]
	v_mfma_f32_16x16x32_bf16 v[16:19], v[156:159], v[204:207], v[16:19]
	v_mfma_f32_16x16x32_bf16 v[4:7], v[148:151], v[212:215], v[4:7]
	v_mfma_f32_16x16x32_bf16 v[0:3], v[156:159], v[212:215], v[0:3]
	s_setprio 0
	s_barrier
	s_add_i32 s86, 0, 0x18000
	s_add_i32 s87, 0, 0x1c000
	v_add_u32_e32 v116, s86, v198
	v_add_u32_e32 v156, s87, v198
	ds_read_b128 v[96:99], v116
	ds_read_b128 v[100:103], v116 offset:1024
	ds_read_b128 v[108:111], v116 offset:2048
	ds_read_b128 v[116:119], v116 offset:3072
	ds_read_b128 v[144:147], v156
	ds_read_b128 v[148:151], v156 offset:1024
	ds_read_b128 v[152:155], v156 offset:2048
	ds_read_b128 v[156:159], v156 offset:3072
	s_add_u32 s46, s46, 0x160000
	s_addc_u32 s47, s47, 0
	s_mov_b32 m0, s50
	v_lshl_add_u64 v[222:223], s[46:47], 0, v[168:169]
	ds_read_b128 v[160:163], v203 offset:32768
	ds_read_b128 v[164:167], v203 offset:33792
	ds_read_b128 v[182:185], v203 offset:34816
	ds_read_b128 v[186:189], v203 offset:35840
	ds_read_b128 v[194:197], v203 offset:36864
	ds_read_b128 v[204:207], v203 offset:37888
	ds_read_b128 v[208:211], v203 offset:38912
	ds_read_b128 v[212:215], v203 offset:39936
	global_load_lds_dwordx4 v[222:223], off
	v_lshl_add_u64 v[222:223], s[46:47], 0, v[172:173]
	s_mov_b32 m0, s51
	s_nop 0
	global_load_lds_dwordx4 v[222:223], off
	s_waitcnt vmcnt(8)
	s_waitcnt lgkmcnt(0)
	s_barrier
	s_setprio 1
	v_mfma_f32_16x16x32_bf16 v[140:143], v[96:99], v[160:163], v[140:143]
	v_mfma_f32_16x16x32_bf16 v[136:139], v[108:111], v[160:163], v[136:139]
	v_mfma_f32_16x16x32_bf16 v[124:127], v[96:99], v[182:185], v[124:127]
	v_mfma_f32_16x16x32_bf16 v[120:123], v[108:111], v[182:185], v[120:123]
	v_mfma_f32_16x16x32_bf16 v[92:95], v[96:99], v[194:197], v[92:95]
	v_mfma_f32_16x16x32_bf16 v[88:91], v[108:111], v[194:197], v[88:91]
	v_mfma_f32_16x16x32_bf16 v[76:79], v[96:99], v[208:211], v[76:79]
	v_mfma_f32_16x16x32_bf16 v[72:75], v[108:111], v[208:211], v[72:75]
	v_mfma_f32_16x16x32_bf16 v[140:143], v[100:103], v[164:167], v[140:143]
	v_mfma_f32_16x16x32_bf16 v[136:139], v[116:119], v[164:167], v[136:139]
	v_mfma_f32_16x16x32_bf16 v[124:127], v[100:103], v[186:189], v[124:127]
	v_mfma_f32_16x16x32_bf16 v[120:123], v[116:119], v[186:189], v[120:123]
	v_mfma_f32_16x16x32_bf16 v[92:95], v[100:103], v[204:207], v[92:95]
	v_mfma_f32_16x16x32_bf16 v[88:91], v[116:119], v[204:207], v[88:91]
	v_mfma_f32_16x16x32_bf16 v[76:79], v[100:103], v[212:215], v[76:79]
	v_mfma_f32_16x16x32_bf16 v[72:75], v[116:119], v[212:215], v[72:75]
	s_setprio 0
	s_setprio 1
	v_mfma_f32_16x16x32_bf16 v[132:135], v[144:147], v[160:163], v[132:135]
	v_mfma_f32_16x16x32_bf16 v[128:131], v[152:155], v[160:163], v[128:131]
	v_mfma_f32_16x16x32_bf16 v[112:115], v[144:147], v[182:185], v[112:115]
	v_mfma_f32_16x16x32_bf16 v[104:107], v[152:155], v[182:185], v[104:107]
	v_mfma_f32_16x16x32_bf16 v[84:87], v[144:147], v[194:197], v[84:87]
	v_mfma_f32_16x16x32_bf16 v[80:83], v[152:155], v[194:197], v[80:83]
	v_mfma_f32_16x16x32_bf16 v[68:71], v[144:147], v[208:211], v[68:71]
	v_mfma_f32_16x16x32_bf16 v[64:67], v[152:155], v[208:211], v[64:67]
	v_mfma_f32_16x16x32_bf16 v[132:135], v[148:151], v[164:167], v[132:135]
	v_mfma_f32_16x16x32_bf16 v[128:131], v[156:159], v[164:167], v[128:131]
	v_mfma_f32_16x16x32_bf16 v[112:115], v[148:151], v[186:189], v[112:115]
	v_mfma_f32_16x16x32_bf16 v[104:107], v[156:159], v[186:189], v[104:107]
	v_mfma_f32_16x16x32_bf16 v[84:87], v[148:151], v[204:207], v[84:87]
	v_mfma_f32_16x16x32_bf16 v[80:83], v[156:159], v[204:207], v[80:83]
	v_mfma_f32_16x16x32_bf16 v[68:71], v[148:151], v[212:215], v[68:71]
	v_mfma_f32_16x16x32_bf16 v[64:67], v[156:159], v[212:215], v[64:67]
	s_setprio 0
	s_barrier
; #define PG8_STAGE(bufoff, gbase, voff) do { _Pragma("unroll") for (int _i = 0; _i < 2; ++_i) \
;         __builtin_amdgcn_global_load_lds((const unsigned*)((const char*)(gbase) + (voff)[_i]), (LAS unsigned*)(lds + (bufoff) + ldsw + _i * 8192), 16, 0, 0); } while (0)
; #define PG8_LDA(dst, b, h) do { _Pragma("unroll") for (int m = 0; m < 4; ++m) _Pragma("unroll") for (int k = 0; k < 2; ++k) dst[m][k] = *(const LAS bf16x8*)(lds + PG8_SA(b, h) + aoff + m * 2048 + k * 1024); } while (0)
; #define PG8_MMA(ai, bj, At, Bt) do { __builtin_amdgcn_s_setprio(1); _Pragma("unroll") for (int m = 0; m < 4; ++m) _Pragma("unroll") for (int n = 0; n < 2; ++n) _Pragma("unroll") for (int k = 0; k < 2; ++k) \
;         acc[ai][bj][m][n] = __builtin_amdgcn_mfma_f32_16x16x32_bf16(Bt[n][k], At[m][k], acc[ai][bj][m][n], 0, 0, 0); __builtin_amdgcn_s_setprio(0); } while (0)
; #define PG8_WAIT_V(n) asm volatile("s_waitcnt vmcnt(" #n ")" ::: "memory")
; #define PG8_WAIT_L(n) asm volatile("s_waitcnt lgkmcnt(" #n ")" ::: "memory")
; #define PG8_BAR __builtin_amdgcn_s_barrier()
; #define PG8_SCHED __builtin_amdgcn_sched_barrier(0)
; template <class Epi, class Sched = StaticOrder, class EpiSub = NoSub, bool FAST = false>
; __device__ __forceinline__ void gemm_phase(LAS unsigned char* lds, const Gemm g, const Sched& S, const Epi& E, const EpiSub& ES = EpiSub()) {
;     ...
;             PG8_LDA(At, 1, 1); PG8_STAGE(PG8_SB(1, 0), b3, voffB); PG8_STAGE(PG8_SB(1, 1), b3 + hstepB, voffB); PG8_STAGE(PG8_SA(1, 0), a3, voffA);
;             PG8_WAIT_V(8); PG8_WAIT_L(0); PG8_BAR; PG8_MMA(1, 0, At, B0); PG8_MMA(1, 1, At, B1); PG8_BAR; PG8_SCHED;
;     ...
;         if constexpr (FAST && PG8_ALIGN) { if (wr == 0) PG8_BAR; }
	s_add_i32 s46, s86, s27
	v_lshl_add_u64 v[190:191], v[190:191], 0, s[16:17]
	s_mov_b32 m0, s46
	ds_read_b128 v[160:163], v203 offset:49152
	ds_read_b128 v[164:167], v203 offset:50176
	ds_read_b128 v[182:185], v203 offset:51200
	ds_read_b128 v[186:189], v203 offset:52224
	ds_read_b128 v[194:197], v203 offset:53248
	ds_read_b128 v[204:207], v203 offset:54272
	ds_read_b128 v[208:211], v203 offset:55296
	ds_read_b128 v[212:215], v203 offset:56320
	global_load_lds_dwordx4 v[190:191], off
	s_add_i32 m0, s46, 0x2000
	s_add_u32 s44, s44, 0x160080
	v_lshl_add_u64 v[190:191], v[216:217], 0, s[16:17]
	s_addc_u32 s45, s45, 0
	s_add_i32 s46, s87, s27
	global_load_lds_dwordx4 v[190:191], off
	v_lshl_add_u64 v[190:191], s[44:45], 0, v[170:171]
	s_mov_b32 m0, s46
	s_nop 0
	global_load_lds_dwordx4 v[190:191], off
	v_lshl_add_u64 v[190:191], s[44:45], 0, v[174:175]
	s_add_i32 m0, s46, 0x2000
	s_nop 0
	global_load_lds_dwordx4 v[190:191], off
	v_lshl_add_u64 v[190:191], v[218:219], 0, s[16:17]
	s_mov_b32 m0, s53
	s_nop 0
	global_load_lds_dwordx4 v[190:191], off
	v_lshl_add_u64 v[190:191], v[220:221], 0, s[16:17]
	s_mov_b32 m0, s54
	s_nop 0
	global_load_lds_dwordx4 v[190:191], off
	s_waitcnt vmcnt(8)
	s_waitcnt lgkmcnt(0)
	s_barrier
	s_setprio 1
	v_mfma_f32_16x16x32_bf16 v[60:63], v[96:99], v[160:163], v[60:63]
	v_mfma_f32_16x16x32_bf16 v[56:59], v[108:111], v[160:163], v[56:59]
	v_mfma_f32_16x16x32_bf16 v[44:47], v[96:99], v[182:185], v[44:47]
	v_mfma_f32_16x16x32_bf16 v[40:43], v[108:111], v[182:185], v[40:43]
	v_mfma_f32_16x16x32_bf16 v[28:31], v[96:99], v[194:197], v[28:31]
	v_mfma_f32_16x16x32_bf16 v[24:27], v[108:111], v[194:197], v[24:27]
	v_mfma_f32_16x16x32_bf16 v[12:15], v[96:99], v[208:211], v[12:15]
	v_mfma_f32_16x16x32_bf16 v[8:11], v[108:111], v[208:211], v[8:11]
	v_mfma_f32_16x16x32_bf16 v[60:63], v[100:103], v[164:167], v[60:63]
	v_mfma_f32_16x16x32_bf16 v[56:59], v[116:119], v[164:167], v[56:59]
	v_mfma_f32_16x16x32_bf16 v[44:47], v[100:103], v[186:189], v[44:47]
	v_mfma_f32_16x16x32_bf16 v[40:43], v[116:119], v[186:189], v[40:43]
	v_mfma_f32_16x16x32_bf16 v[28:31], v[100:103], v[204:207], v[28:31]
	v_mfma_f32_16x16x32_bf16 v[24:27], v[116:119], v[204:207], v[24:27]
	v_mfma_f32_16x16x32_bf16 v[12:15], v[100:103], v[212:215], v[12:15]
	v_mfma_f32_16x16x32_bf16 v[8:11], v[116:119], v[212:215], v[8:11]
	s_setprio 0
	s_setprio 1
	v_mfma_f32_16x16x32_bf16 v[52:55], v[144:147], v[160:163], v[52:55]
	v_mfma_f32_16x16x32_bf16 v[48:51], v[152:155], v[160:163], v[48:51]
	v_mfma_f32_16x16x32_bf16 v[36:39], v[144:147], v[182:185], v[36:39]
	v_mfma_f32_16x16x32_bf16 v[32:35], v[152:155], v[182:185], v[32:35]
	v_mfma_f32_16x16x32_bf16 v[20:23], v[144:147], v[194:197], v[20:23]
	v_mfma_f32_16x16x32_bf16 v[16:19], v[152:155], v[194:197], v[16:19]
	v_mfma_f32_16x16x32_bf16 v[4:7], v[144:147], v[208:211], v[4:7]
	v_mfma_f32_16x16x32_bf16 v[0:3], v[152:155], v[208:211], v[0:3]
	v_mfma_f32_16x16x32_bf16 v[52:55], v[148:151], v[164:167], v[52:55]
	v_mfma_f32_16x16x32_bf16 v[48:51], v[156:159], v[164:167], v[48:51]
	v_mfma_f32_16x16x32_bf16 v[36:39], v[148:151], v[186:189], v[36:39]
	v_mfma_f32_16x16x32_bf16 v[32:35], v[156:159], v[186:189], v[32:35]
	v_mfma_f32_16x16x32_bf16 v[20:23], v[148:151], v[204:207], v[20:23]
	v_mfma_f32_16x16x32_bf16 v[16:19], v[156:159], v[204:207], v[16:19]
	v_mfma_f32_16x16x32_bf16 v[4:7], v[148:151], v[212:215], v[4:7]
	v_mfma_f32_16x16x32_bf16 v[0:3], v[156:159], v[212:215], v[0:3]
	s_setprio 0
	s_barrier
	s_add_u32 s42, s42, 0x100
	s_addc_u32 s43, s43, 0
	s_add_u32 s83, s83, 0x100
	s_addc_u32 s84, s84, 0
	s_cmp_ge_u32 s85, s70
	s_mov_b32 s46, s85
	s_cbranch_scc0 .LBB0_1079
	s_and_b64 vcc, exec, s[18:19]
	s_cbranch_vccz .LBB0_1082
	s_barrier
